# removed every s_setprio from the six GEMM K-loops (on top of the P0 weight-copy rewrite)
# speedup vs baseline: 1.0172x; 1.0069x over previous
.LBB0_237:
	ds_read_b128 v[150:153], v147
	ds_read_b128 v[154:157], v147 offset:1024
	ds_read_b128 v[158:161], v147 offset:2048
	ds_read_b128 v[162:165], v147 offset:3072
	ds_read_b128 v[166:169], v148
	ds_read_b128 v[170:173], v148 offset:1024
	ds_read_b128 v[174:177], v148 offset:2048
	ds_read_b128 v[178:181], v148 offset:3072
	s_add_u32 s22, s20, 0xfffc0080
	s_addc_u32 s23, s21, -1
	s_cmp_eq_u32 s48, 12
	s_cselect_b32 s25, s13, s23
	s_cselect_b32 s24, s44, s22
	s_cselect_b32 s23, s11, s47
	s_cselect_b32 s22, s45, s46
	v_lshl_add_u64 v[206:207], s[20:21], 0, v[136:137]
	s_add_i32 m0, s19, 0xc000
	ds_read_b128 v[182:185], v149
	ds_read_b128 v[186:189], v149 offset:1024
	ds_read_b128 v[190:193], v149 offset:2048
	ds_read_b128 v[194:197], v149 offset:3072
	ds_read_b128 v[198:201], v149 offset:4096
	ds_read_b128 v[202:205], v149 offset:5120
	ds_read_b128 v[210:213], v149 offset:6144
	ds_read_b128 v[214:217], v149 offset:7168
	global_load_lds_dwordx4 v[206:207], off
	v_lshl_add_u64 v[206:207], s[20:21], 0, v[138:139]
	s_add_i32 m0, s19, 0xe000
	s_nop 0
	global_load_lds_dwordx4 v[206:207], off
	s_waitcnt vmcnt(8)
	s_waitcnt lgkmcnt(0)
	s_barrier
	s_waitcnt lgkmcnt(0)
	v_mfma_f32_16x16x32_bf16 v[124:127], v[150:153], v[182:185], v[124:127]
	v_mfma_f32_16x16x32_bf16 v[120:123], v[158:161], v[182:185], v[120:123]
	v_mfma_f32_16x16x32_bf16 v[108:111], v[150:153], v[190:193], v[108:111]
	v_mfma_f32_16x16x32_bf16 v[104:107], v[158:161], v[190:193], v[104:107]
	v_mfma_f32_16x16x32_bf16 v[92:95], v[150:153], v[198:201], v[92:95]
	v_mfma_f32_16x16x32_bf16 v[88:91], v[158:161], v[198:201], v[88:91]
	v_mfma_f32_16x16x32_bf16 v[76:79], v[150:153], v[210:213], v[76:79]
	v_mfma_f32_16x16x32_bf16 v[72:75], v[158:161], v[210:213], v[72:75]
	v_mfma_f32_16x16x32_bf16 v[124:127], v[154:157], v[186:189], v[124:127]
	v_mfma_f32_16x16x32_bf16 v[120:123], v[162:165], v[186:189], v[120:123]
	v_mfma_f32_16x16x32_bf16 v[108:111], v[154:157], v[194:197], v[108:111]
	v_mfma_f32_16x16x32_bf16 v[104:107], v[162:165], v[194:197], v[104:107]
	v_mfma_f32_16x16x32_bf16 v[92:95], v[154:157], v[202:205], v[92:95]
	v_mfma_f32_16x16x32_bf16 v[88:91], v[162:165], v[202:205], v[88:91]
	v_mfma_f32_16x16x32_bf16 v[76:79], v[154:157], v[214:217], v[76:79]
	v_mfma_f32_16x16x32_bf16 v[72:75], v[162:165], v[214:217], v[72:75]
	v_mfma_f32_16x16x32_bf16 v[116:119], v[166:169], v[182:185], v[116:119]
	v_mfma_f32_16x16x32_bf16 v[112:115], v[174:177], v[182:185], v[112:115]
	v_mfma_f32_16x16x32_bf16 v[100:103], v[166:169], v[190:193], v[100:103]
	v_mfma_f32_16x16x32_bf16 v[96:99], v[174:177], v[190:193], v[96:99]
	v_mfma_f32_16x16x32_bf16 v[84:87], v[166:169], v[198:201], v[84:87]
	v_mfma_f32_16x16x32_bf16 v[80:83], v[174:177], v[198:201], v[80:83]
	v_mfma_f32_16x16x32_bf16 v[68:71], v[166:169], v[210:213], v[68:71]
	v_mfma_f32_16x16x32_bf16 v[64:67], v[174:177], v[210:213], v[64:67]
	v_mfma_f32_16x16x32_bf16 v[116:119], v[170:173], v[186:189], v[116:119]
	v_mfma_f32_16x16x32_bf16 v[112:115], v[178:181], v[186:189], v[112:115]
	v_mfma_f32_16x16x32_bf16 v[100:103], v[170:173], v[194:197], v[100:103]
	v_mfma_f32_16x16x32_bf16 v[96:99], v[178:181], v[194:197], v[96:99]
	v_mfma_f32_16x16x32_bf16 v[84:87], v[170:173], v[202:205], v[84:87]
	v_mfma_f32_16x16x32_bf16 v[80:83], v[178:181], v[202:205], v[80:83]
	v_mfma_f32_16x16x32_bf16 v[68:71], v[170:173], v[214:217], v[68:71]
	v_mfma_f32_16x16x32_bf16 v[64:67], v[178:181], v[214:217], v[64:67]
	s_barrier
	s_add_i32 s49, s40, s28
	v_lshl_add_u64 v[206:207], s[22:23], 0, v[132:133]
	s_mov_b32 m0, s49
	ds_read_b128 v[182:185], v149 offset:16384
	ds_read_b128 v[186:189], v149 offset:17408
	ds_read_b128 v[190:193], v149 offset:18432
	ds_read_b128 v[194:197], v149 offset:19456
	ds_read_b128 v[198:201], v149 offset:20480
	ds_read_b128 v[202:205], v149 offset:21504
	ds_read_b128 v[210:213], v149 offset:22528
	ds_read_b128 v[214:217], v149 offset:23552
	global_load_lds_dwordx4 v[206:207], off
	s_add_i32 m0, s49, 0x2000
	s_add_u32 s50, s22, 0x40000
	v_lshl_add_u64 v[218:219], s[22:23], 0, v[128:129]
	s_addc_u32 s51, s23, 0
	s_add_i32 s49, s41, s28
	global_load_lds_dwordx4 v[218:219], off
	v_lshl_add_u64 v[220:221], s[50:51], 0, v[132:133]
	s_mov_b32 m0, s49
	v_lshl_add_u64 v[222:223], s[24:25], 0, v[130:131]
	global_load_lds_dwordx4 v[220:221], off
	v_lshl_add_u64 v[220:221], s[50:51], 0, v[128:129]
	s_add_i32 m0, s49, 0x2000
	s_nop 0
	global_load_lds_dwordx4 v[220:221], off
	v_lshl_add_u64 v[220:221], s[24:25], 0, v[134:135]
	s_mov_b32 m0, s19
	s_nop 0
	global_load_lds_dwordx4 v[220:221], off
	s_mov_b32 m0, s31
	s_nop 0
	global_load_lds_dwordx4 v[222:223], off
	s_waitcnt vmcnt(8)
	s_waitcnt lgkmcnt(0)
	s_barrier
	s_waitcnt lgkmcnt(0)
	v_mfma_f32_16x16x32_bf16 v[60:63], v[150:153], v[182:185], v[60:63]
	v_mfma_f32_16x16x32_bf16 v[56:59], v[158:161], v[182:185], v[56:59]
	v_mfma_f32_16x16x32_bf16 v[44:47], v[150:153], v[190:193], v[44:47]
	v_mfma_f32_16x16x32_bf16 v[40:43], v[158:161], v[190:193], v[40:43]
	v_mfma_f32_16x16x32_bf16 v[28:31], v[150:153], v[198:201], v[28:31]
	v_mfma_f32_16x16x32_bf16 v[24:27], v[158:161], v[198:201], v[24:27]
	v_mfma_f32_16x16x32_bf16 v[12:15], v[150:153], v[210:213], v[12:15]
	v_mfma_f32_16x16x32_bf16 v[8:11], v[158:161], v[210:213], v[8:11]
	v_mfma_f32_16x16x32_bf16 v[60:63], v[154:157], v[186:189], v[60:63]
	v_mfma_f32_16x16x32_bf16 v[56:59], v[162:165], v[186:189], v[56:59]
	v_mfma_f32_16x16x32_bf16 v[44:47], v[154:157], v[194:197], v[44:47]
	v_mfma_f32_16x16x32_bf16 v[40:43], v[162:165], v[194:197], v[40:43]
	v_mfma_f32_16x16x32_bf16 v[28:31], v[154:157], v[202:205], v[28:31]
	v_mfma_f32_16x16x32_bf16 v[24:27], v[162:165], v[202:205], v[24:27]
	v_mfma_f32_16x16x32_bf16 v[12:15], v[154:157], v[214:217], v[12:15]
	v_mfma_f32_16x16x32_bf16 v[8:11], v[162:165], v[214:217], v[8:11]
	v_mfma_f32_16x16x32_bf16 v[52:55], v[166:169], v[182:185], v[52:55]
	v_mfma_f32_16x16x32_bf16 v[48:51], v[174:177], v[182:185], v[48:51]
	v_mfma_f32_16x16x32_bf16 v[36:39], v[166:169], v[190:193], v[36:39]
	v_mfma_f32_16x16x32_bf16 v[32:35], v[174:177], v[190:193], v[32:35]
	v_mfma_f32_16x16x32_bf16 v[20:23], v[166:169], v[198:201], v[20:23]
	v_mfma_f32_16x16x32_bf16 v[16:19], v[174:177], v[198:201], v[16:19]
	v_mfma_f32_16x16x32_bf16 v[4:7], v[166:169], v[210:213], v[4:7]
	v_mfma_f32_16x16x32_bf16 v[0:3], v[174:177], v[210:213], v[0:3]
	v_mfma_f32_16x16x32_bf16 v[52:55], v[170:173], v[186:189], v[52:55]
	v_mfma_f32_16x16x32_bf16 v[48:51], v[178:181], v[186:189], v[48:51]
	v_mfma_f32_16x16x32_bf16 v[36:39], v[170:173], v[194:197], v[36:39]
	v_mfma_f32_16x16x32_bf16 v[32:35], v[178:181], v[194:197], v[32:35]
	v_mfma_f32_16x16x32_bf16 v[20:23], v[170:173], v[202:205], v[20:23]
	v_mfma_f32_16x16x32_bf16 v[16:19], v[178:181], v[202:205], v[16:19]
	v_mfma_f32_16x16x32_bf16 v[4:7], v[170:173], v[214:217], v[4:7]
	v_mfma_f32_16x16x32_bf16 v[0:3], v[178:181], v[214:217], v[0:3]
	s_barrier
	s_add_i32 s49, 0, 0x18000
	s_add_i32 s50, 0, 0x1c000
	v_add_u32_e32 v162, s49, v145
	v_add_u32_e32 v178, s50, v145
	ds_read_b128 v[150:153], v162
	ds_read_b128 v[154:157], v162 offset:1024
	ds_read_b128 v[158:161], v162 offset:2048
	ds_read_b128 v[162:165], v162 offset:3072
	ds_read_b128 v[166:169], v178
	ds_read_b128 v[170:173], v178 offset:1024
	ds_read_b128 v[174:177], v178 offset:2048
	ds_read_b128 v[178:181], v178 offset:3072
	s_add_u32 s24, s24, 0x40000
	s_addc_u32 s25, s25, 0
	s_mov_b32 m0, s33
	v_lshl_add_u64 v[224:225], s[24:25], 0, v[134:135]
	ds_read_b128 v[182:185], v149 offset:32768
	ds_read_b128 v[186:189], v149 offset:33792
	ds_read_b128 v[190:193], v149 offset:34816
	ds_read_b128 v[194:197], v149 offset:35840
	ds_read_b128 v[198:201], v149 offset:36864
	ds_read_b128 v[202:205], v149 offset:37888
	ds_read_b128 v[210:213], v149 offset:38912
	ds_read_b128 v[214:217], v149 offset:39936
	global_load_lds_dwordx4 v[224:225], off
	v_lshl_add_u64 v[224:225], s[24:25], 0, v[130:131]
	s_mov_b32 m0, s34
	s_nop 0
	global_load_lds_dwordx4 v[224:225], off
	s_waitcnt vmcnt(8)
	s_waitcnt lgkmcnt(0)
	s_barrier
	s_waitcnt lgkmcnt(0)
	v_mfma_f32_16x16x32_bf16 v[124:127], v[150:153], v[182:185], v[124:127]
	v_mfma_f32_16x16x32_bf16 v[120:123], v[158:161], v[182:185], v[120:123]
	v_mfma_f32_16x16x32_bf16 v[108:111], v[150:153], v[190:193], v[108:111]
	v_mfma_f32_16x16x32_bf16 v[104:107], v[158:161], v[190:193], v[104:107]
	v_mfma_f32_16x16x32_bf16 v[92:95], v[150:153], v[198:201], v[92:95]
	v_mfma_f32_16x16x32_bf16 v[88:91], v[158:161], v[198:201], v[88:91]
	v_mfma_f32_16x16x32_bf16 v[76:79], v[150:153], v[210:213], v[76:79]
	v_mfma_f32_16x16x32_bf16 v[72:75], v[158:161], v[210:213], v[72:75]
	v_mfma_f32_16x16x32_bf16 v[124:127], v[154:157], v[186:189], v[124:127]
	v_mfma_f32_16x16x32_bf16 v[120:123], v[162:165], v[186:189], v[120:123]
	v_mfma_f32_16x16x32_bf16 v[108:111], v[154:157], v[194:197], v[108:111]
	v_mfma_f32_16x16x32_bf16 v[104:107], v[162:165], v[194:197], v[104:107]
	v_mfma_f32_16x16x32_bf16 v[92:95], v[154:157], v[202:205], v[92:95]
	v_mfma_f32_16x16x32_bf16 v[88:91], v[162:165], v[202:205], v[88:91]
	v_mfma_f32_16x16x32_bf16 v[76:79], v[154:157], v[214:217], v[76:79]
	v_mfma_f32_16x16x32_bf16 v[72:75], v[162:165], v[214:217], v[72:75]
	v_mfma_f32_16x16x32_bf16 v[116:119], v[166:169], v[182:185], v[116:119]
	v_mfma_f32_16x16x32_bf16 v[112:115], v[174:177], v[182:185], v[112:115]
	v_mfma_f32_16x16x32_bf16 v[100:103], v[166:169], v[190:193], v[100:103]
	v_mfma_f32_16x16x32_bf16 v[96:99], v[174:177], v[190:193], v[96:99]
	v_mfma_f32_16x16x32_bf16 v[84:87], v[166:169], v[198:201], v[84:87]
	v_mfma_f32_16x16x32_bf16 v[80:83], v[174:177], v[198:201], v[80:83]
	v_mfma_f32_16x16x32_bf16 v[68:71], v[166:169], v[210:213], v[68:71]
	v_mfma_f32_16x16x32_bf16 v[64:67], v[174:177], v[210:213], v[64:67]
	v_mfma_f32_16x16x32_bf16 v[116:119], v[170:173], v[186:189], v[116:119]
	v_mfma_f32_16x16x32_bf16 v[112:115], v[178:181], v[186:189], v[112:115]
	v_mfma_f32_16x16x32_bf16 v[100:103], v[170:173], v[194:197], v[100:103]
	v_mfma_f32_16x16x32_bf16 v[96:99], v[178:181], v[194:197], v[96:99]
	v_mfma_f32_16x16x32_bf16 v[84:87], v[170:173], v[202:205], v[84:87]
	v_mfma_f32_16x16x32_bf16 v[80:83], v[178:181], v[202:205], v[80:83]
	v_mfma_f32_16x16x32_bf16 v[68:71], v[170:173], v[214:217], v[68:71]
	v_mfma_f32_16x16x32_bf16 v[64:67], v[178:181], v[214:217], v[64:67]
	s_barrier
	s_add_i32 s24, s49, s28
	v_lshl_add_u64 v[206:207], v[206:207], 0, s[6:7]
	s_mov_b32 m0, s24
	ds_read_b128 v[182:185], v149 offset:49152
	ds_read_b128 v[186:189], v149 offset:50176
	ds_read_b128 v[190:193], v149 offset:51200
	ds_read_b128 v[194:197], v149 offset:52224
	ds_read_b128 v[198:201], v149 offset:53248
	ds_read_b128 v[202:205], v149 offset:54272
	ds_read_b128 v[210:213], v149 offset:55296
	ds_read_b128 v[214:217], v149 offset:56320
	global_load_lds_dwordx4 v[206:207], off
	s_add_i32 m0, s24, 0x2000
	s_add_u32 s22, s22, 0x40080
	v_lshl_add_u64 v[206:207], v[218:219], 0, s[6:7]
	s_addc_u32 s23, s23, 0
	s_add_i32 s24, s50, s28
	global_load_lds_dwordx4 v[206:207], off
	v_lshl_add_u64 v[206:207], s[22:23], 0, v[132:133]
	s_mov_b32 m0, s24
	s_nop 0
	global_load_lds_dwordx4 v[206:207], off
	v_lshl_add_u64 v[206:207], s[22:23], 0, v[128:129]
	s_add_i32 m0, s24, 0x2000
	s_nop 0
	global_load_lds_dwordx4 v[206:207], off
	v_lshl_add_u64 v[206:207], v[220:221], 0, s[6:7]
	s_mov_b32 m0, s36
	s_nop 0
	global_load_lds_dwordx4 v[206:207], off
	v_lshl_add_u64 v[206:207], v[222:223], 0, s[6:7]
	s_mov_b32 m0, s37
	s_nop 0
	global_load_lds_dwordx4 v[206:207], off
	s_waitcnt vmcnt(8)
	s_waitcnt lgkmcnt(0)
	s_barrier
	s_waitcnt lgkmcnt(0)
	v_mfma_f32_16x16x32_bf16 v[60:63], v[150:153], v[182:185], v[60:63]
	v_mfma_f32_16x16x32_bf16 v[56:59], v[158:161], v[182:185], v[56:59]
	v_mfma_f32_16x16x32_bf16 v[44:47], v[150:153], v[190:193], v[44:47]
	v_mfma_f32_16x16x32_bf16 v[40:43], v[158:161], v[190:193], v[40:43]
	v_mfma_f32_16x16x32_bf16 v[28:31], v[150:153], v[198:201], v[28:31]
	v_mfma_f32_16x16x32_bf16 v[24:27], v[158:161], v[198:201], v[24:27]
	v_mfma_f32_16x16x32_bf16 v[12:15], v[150:153], v[210:213], v[12:15]
	v_mfma_f32_16x16x32_bf16 v[8:11], v[158:161], v[210:213], v[8:11]
	v_mfma_f32_16x16x32_bf16 v[60:63], v[154:157], v[186:189], v[60:63]
	v_mfma_f32_16x16x32_bf16 v[56:59], v[162:165], v[186:189], v[56:59]
	v_mfma_f32_16x16x32_bf16 v[44:47], v[154:157], v[194:197], v[44:47]
	v_mfma_f32_16x16x32_bf16 v[40:43], v[162:165], v[194:197], v[40:43]
	v_mfma_f32_16x16x32_bf16 v[28:31], v[154:157], v[202:205], v[28:31]
	v_mfma_f32_16x16x32_bf16 v[24:27], v[162:165], v[202:205], v[24:27]
	v_mfma_f32_16x16x32_bf16 v[12:15], v[154:157], v[214:217], v[12:15]
	v_mfma_f32_16x16x32_bf16 v[8:11], v[162:165], v[214:217], v[8:11]
	v_mfma_f32_16x16x32_bf16 v[52:55], v[166:169], v[182:185], v[52:55]
	v_mfma_f32_16x16x32_bf16 v[48:51], v[174:177], v[182:185], v[48:51]
	v_mfma_f32_16x16x32_bf16 v[36:39], v[166:169], v[190:193], v[36:39]
	v_mfma_f32_16x16x32_bf16 v[32:35], v[174:177], v[190:193], v[32:35]
	v_mfma_f32_16x16x32_bf16 v[20:23], v[166:169], v[198:201], v[20:23]
	v_mfma_f32_16x16x32_bf16 v[16:19], v[174:177], v[198:201], v[16:19]
	v_mfma_f32_16x16x32_bf16 v[4:7], v[166:169], v[210:213], v[4:7]
	v_mfma_f32_16x16x32_bf16 v[0:3], v[174:177], v[210:213], v[0:3]
	v_mfma_f32_16x16x32_bf16 v[52:55], v[170:173], v[186:189], v[52:55]
	v_mfma_f32_16x16x32_bf16 v[48:51], v[178:181], v[186:189], v[48:51]
	v_mfma_f32_16x16x32_bf16 v[36:39], v[170:173], v[194:197], v[36:39]
	v_mfma_f32_16x16x32_bf16 v[32:35], v[178:181], v[194:197], v[32:35]
	v_mfma_f32_16x16x32_bf16 v[20:23], v[170:173], v[202:205], v[20:23]
	v_mfma_f32_16x16x32_bf16 v[16:19], v[178:181], v[202:205], v[16:19]
	v_mfma_f32_16x16x32_bf16 v[4:7], v[170:173], v[214:217], v[4:7]
	v_mfma_f32_16x16x32_bf16 v[0:3], v[178:181], v[214:217], v[0:3]
	s_barrier
	s_add_i32 s48, s48, 2
	s_add_u32 s20, s20, 0x100
	s_addc_u32 s21, s21, 0
	s_add_u32 s46, s46, 0x100
	s_addc_u32 s47, s47, 0
	s_cmp_gt_u32 s48, 13
	s_cbranch_scc0 .LBB0_237
	s_and_b64 vcc, exec, s[8:9]
	s_cbranch_vccz .LBB0_240
	s_barrier

.LBB0_324:
	ds_read_b128 v[128:131], v240
	ds_read_b128 v[132:135], v240 offset:1024
	ds_read_b128 v[136:139], v240 offset:2048
	ds_read_b128 v[140:143], v240 offset:3072
	ds_read_b128 v[144:147], v241
	ds_read_b128 v[148:151], v241 offset:1024
	ds_read_b128 v[152:155], v241 offset:2048
	ds_read_b128 v[156:159], v241 offset:3072
	s_add_u32 s18, s4, 0xfff50080
	s_addc_u32 s19, s5, -1
	s_cmp_eq_u32 s44, 40
	s_cselect_b32 s21, s17, s19
	s_cselect_b32 s20, s16, s18
	s_cselect_b32 s19, s7, s43
	s_cselect_b32 s18, s6, s42
	v_lshl_add_u64 v[192:193], s[4:5], 0, v[218:219]
	s_add_i32 m0, s27, 0xc000
	ds_read_b128 v[160:163], v242
	ds_read_b128 v[164:167], v242 offset:1024
	ds_read_b128 v[168:171], v242 offset:2048
	ds_read_b128 v[172:175], v242 offset:3072
	ds_read_b128 v[176:179], v242 offset:4096
	ds_read_b128 v[180:183], v242 offset:5120
	ds_read_b128 v[184:187], v242 offset:6144
	ds_read_b128 v[188:191], v242 offset:7168
	global_load_lds_dwordx4 v[192:193], off
	v_lshl_add_u64 v[192:193], s[4:5], 0, v[220:221]
	s_add_i32 m0, s27, 0xe000
	s_nop 0
	global_load_lds_dwordx4 v[192:193], off
	s_waitcnt vmcnt(8)
	s_waitcnt lgkmcnt(0)
	s_barrier
	s_waitcnt lgkmcnt(0)
	v_mfma_f32_16x16x32_bf16 v[124:127], v[128:131], v[160:163], v[124:127]
	v_mfma_f32_16x16x32_bf16 v[120:123], v[136:139], v[160:163], v[120:123]
	v_mfma_f32_16x16x32_bf16 v[116:119], v[128:131], v[168:171], v[116:119]
	v_mfma_f32_16x16x32_bf16 v[112:115], v[136:139], v[168:171], v[112:115]
	v_mfma_f32_16x16x32_bf16 v[108:111], v[128:131], v[176:179], v[108:111]
	v_mfma_f32_16x16x32_bf16 v[100:103], v[136:139], v[176:179], v[100:103]
	v_mfma_f32_16x16x32_bf16 v[80:83], v[128:131], v[184:187], v[80:83]
	v_mfma_f32_16x16x32_bf16 v[72:75], v[136:139], v[184:187], v[72:75]
	v_mfma_f32_16x16x32_bf16 v[124:127], v[132:135], v[164:167], v[124:127]
	v_mfma_f32_16x16x32_bf16 v[120:123], v[140:143], v[164:167], v[120:123]
	v_mfma_f32_16x16x32_bf16 v[116:119], v[132:135], v[172:175], v[116:119]
	v_mfma_f32_16x16x32_bf16 v[112:115], v[140:143], v[172:175], v[112:115]
	v_mfma_f32_16x16x32_bf16 v[108:111], v[132:135], v[180:183], v[108:111]
	v_mfma_f32_16x16x32_bf16 v[100:103], v[140:143], v[180:183], v[100:103]
	v_mfma_f32_16x16x32_bf16 v[80:83], v[132:135], v[188:191], v[80:83]
	v_mfma_f32_16x16x32_bf16 v[72:75], v[140:143], v[188:191], v[72:75]
	v_mfma_f32_16x16x32_bf16 v[104:107], v[144:147], v[160:163], v[104:107]
	v_mfma_f32_16x16x32_bf16 v[96:99], v[152:155], v[160:163], v[96:99]
	v_mfma_f32_16x16x32_bf16 v[92:95], v[144:147], v[168:171], v[92:95]
	v_mfma_f32_16x16x32_bf16 v[88:91], v[152:155], v[168:171], v[88:91]
	v_mfma_f32_16x16x32_bf16 v[84:87], v[144:147], v[176:179], v[84:87]
	v_mfma_f32_16x16x32_bf16 v[76:79], v[152:155], v[176:179], v[76:79]
	v_mfma_f32_16x16x32_bf16 v[68:71], v[144:147], v[184:187], v[68:71]
	v_mfma_f32_16x16x32_bf16 v[64:67], v[152:155], v[184:187], v[64:67]
	v_mfma_f32_16x16x32_bf16 v[104:107], v[148:151], v[164:167], v[104:107]
	v_mfma_f32_16x16x32_bf16 v[96:99], v[156:159], v[164:167], v[96:99]
	v_mfma_f32_16x16x32_bf16 v[92:95], v[148:151], v[172:175], v[92:95]
	v_mfma_f32_16x16x32_bf16 v[88:91], v[156:159], v[172:175], v[88:91]
	v_mfma_f32_16x16x32_bf16 v[84:87], v[148:151], v[180:183], v[84:87]
	v_mfma_f32_16x16x32_bf16 v[76:79], v[156:159], v[180:183], v[76:79]
	v_mfma_f32_16x16x32_bf16 v[68:71], v[148:151], v[188:191], v[68:71]
	v_mfma_f32_16x16x32_bf16 v[64:67], v[156:159], v[188:191], v[64:67]
	s_barrier
	s_add_i32 s45, s38, s26
	v_lshl_add_u64 v[192:193], s[18:19], 0, v[212:213]
	s_mov_b32 m0, s45
	ds_read_b128 v[160:163], v242 offset:16384
	ds_read_b128 v[164:167], v242 offset:17408
	ds_read_b128 v[168:171], v242 offset:18432
	ds_read_b128 v[172:175], v242 offset:19456
	ds_read_b128 v[176:179], v242 offset:20480
	ds_read_b128 v[180:183], v242 offset:21504
	ds_read_b128 v[184:187], v242 offset:22528
	ds_read_b128 v[188:191], v242 offset:23552
	global_load_lds_dwordx4 v[192:193], off
	s_add_i32 m0, s45, 0x2000
	s_add_u32 s46, s18, 0xb0000
	v_lshl_add_u64 v[194:195], s[18:19], 0, v[216:217]
	s_addc_u32 s47, s19, 0
	s_add_i32 s45, s39, s26
	global_load_lds_dwordx4 v[194:195], off
	v_lshl_add_u64 v[196:197], s[46:47], 0, v[212:213]
	s_mov_b32 m0, s45
	v_lshl_add_u64 v[198:199], s[20:21], 0, v[214:215]
	global_load_lds_dwordx4 v[196:197], off
	v_lshl_add_u64 v[196:197], s[46:47], 0, v[216:217]
	s_add_i32 m0, s45, 0x2000
	s_nop 0
	global_load_lds_dwordx4 v[196:197], off
	v_lshl_add_u64 v[196:197], s[20:21], 0, v[210:211]
	s_mov_b32 m0, s27
	s_nop 0
	global_load_lds_dwordx4 v[196:197], off
	s_mov_b32 m0, s28
	s_nop 0
	global_load_lds_dwordx4 v[198:199], off
	s_waitcnt vmcnt(8)
	s_waitcnt lgkmcnt(0)
	s_barrier
	s_waitcnt lgkmcnt(0)
	v_mfma_f32_16x16x32_bf16 v[60:63], v[128:131], v[160:163], v[60:63]
	v_mfma_f32_16x16x32_bf16 v[56:59], v[136:139], v[160:163], v[56:59]
	v_mfma_f32_16x16x32_bf16 v[52:55], v[128:131], v[168:171], v[52:55]
	v_mfma_f32_16x16x32_bf16 v[48:51], v[136:139], v[168:171], v[48:51]
	v_mfma_f32_16x16x32_bf16 v[44:47], v[128:131], v[176:179], v[44:47]
	v_mfma_f32_16x16x32_bf16 v[36:39], v[136:139], v[176:179], v[36:39]
	v_mfma_f32_16x16x32_bf16 v[20:23], v[128:131], v[184:187], v[20:23]
	v_mfma_f32_16x16x32_bf16 v[12:15], v[136:139], v[184:187], v[12:15]
	v_mfma_f32_16x16x32_bf16 v[60:63], v[132:135], v[164:167], v[60:63]
	v_mfma_f32_16x16x32_bf16 v[56:59], v[140:143], v[164:167], v[56:59]
	v_mfma_f32_16x16x32_bf16 v[52:55], v[132:135], v[172:175], v[52:55]
	v_mfma_f32_16x16x32_bf16 v[48:51], v[140:143], v[172:175], v[48:51]
	v_mfma_f32_16x16x32_bf16 v[44:47], v[132:135], v[180:183], v[44:47]
	v_mfma_f32_16x16x32_bf16 v[36:39], v[140:143], v[180:183], v[36:39]
	v_mfma_f32_16x16x32_bf16 v[20:23], v[132:135], v[188:191], v[20:23]
	v_mfma_f32_16x16x32_bf16 v[12:15], v[140:143], v[188:191], v[12:15]
	v_mfma_f32_16x16x32_bf16 v[40:43], v[144:147], v[160:163], v[40:43]
	v_mfma_f32_16x16x32_bf16 v[32:35], v[152:155], v[160:163], v[32:35]
	v_mfma_f32_16x16x32_bf16 v[28:31], v[144:147], v[168:171], v[28:31]
	v_mfma_f32_16x16x32_bf16 v[24:27], v[152:155], v[168:171], v[24:27]
	v_mfma_f32_16x16x32_bf16 v[16:19], v[144:147], v[176:179], v[16:19]
	v_mfma_f32_16x16x32_bf16 v[8:11], v[152:155], v[176:179], v[8:11]
	v_mfma_f32_16x16x32_bf16 v[4:7], v[144:147], v[184:187], v[4:7]
	v_mfma_f32_16x16x32_bf16 v[0:3], v[152:155], v[184:187], v[0:3]
	v_mfma_f32_16x16x32_bf16 v[40:43], v[148:151], v[164:167], v[40:43]
	v_mfma_f32_16x16x32_bf16 v[32:35], v[156:159], v[164:167], v[32:35]
	v_mfma_f32_16x16x32_bf16 v[28:31], v[148:151], v[172:175], v[28:31]
	v_mfma_f32_16x16x32_bf16 v[24:27], v[156:159], v[172:175], v[24:27]
	v_mfma_f32_16x16x32_bf16 v[16:19], v[148:151], v[180:183], v[16:19]
	v_mfma_f32_16x16x32_bf16 v[8:11], v[156:159], v[180:183], v[8:11]
	v_mfma_f32_16x16x32_bf16 v[4:7], v[148:151], v[188:191], v[4:7]
	v_mfma_f32_16x16x32_bf16 v[0:3], v[156:159], v[188:191], v[0:3]
	s_barrier
	s_add_i32 s45, 0, 0x18000
	s_add_i32 s46, 0, 0x1c000
	v_add_u32_e32 v140, s45, v238
	v_add_u32_e32 v156, s46, v238
	ds_read_b128 v[128:131], v140
	ds_read_b128 v[132:135], v140 offset:1024
	ds_read_b128 v[136:139], v140 offset:2048
	ds_read_b128 v[140:143], v140 offset:3072
	ds_read_b128 v[144:147], v156
	ds_read_b128 v[148:151], v156 offset:1024
	ds_read_b128 v[152:155], v156 offset:2048
	ds_read_b128 v[156:159], v156 offset:3072
	s_add_u32 s20, s20, 0xb0000
	s_addc_u32 s21, s21, 0
	s_mov_b32 m0, s29
	v_lshl_add_u64 v[200:201], s[20:21], 0, v[210:211]
	ds_read_b128 v[160:163], v242 offset:32768
	ds_read_b128 v[164:167], v242 offset:33792
	ds_read_b128 v[168:171], v242 offset:34816
	ds_read_b128 v[172:175], v242 offset:35840
	ds_read_b128 v[176:179], v242 offset:36864
	ds_read_b128 v[180:183], v242 offset:37888
	ds_read_b128 v[184:187], v242 offset:38912
	ds_read_b128 v[188:191], v242 offset:39936
	global_load_lds_dwordx4 v[200:201], off
	v_lshl_add_u64 v[200:201], s[20:21], 0, v[214:215]
	s_mov_b32 m0, s30
	s_nop 0
	global_load_lds_dwordx4 v[200:201], off
	s_waitcnt vmcnt(8)
	s_waitcnt lgkmcnt(0)
	s_barrier
	s_waitcnt lgkmcnt(0)
	v_mfma_f32_16x16x32_bf16 v[124:127], v[128:131], v[160:163], v[124:127]
	v_mfma_f32_16x16x32_bf16 v[120:123], v[136:139], v[160:163], v[120:123]
	v_mfma_f32_16x16x32_bf16 v[116:119], v[128:131], v[168:171], v[116:119]
	v_mfma_f32_16x16x32_bf16 v[112:115], v[136:139], v[168:171], v[112:115]
	v_mfma_f32_16x16x32_bf16 v[108:111], v[128:131], v[176:179], v[108:111]
	v_mfma_f32_16x16x32_bf16 v[100:103], v[136:139], v[176:179], v[100:103]
	v_mfma_f32_16x16x32_bf16 v[80:83], v[128:131], v[184:187], v[80:83]
	v_mfma_f32_16x16x32_bf16 v[72:75], v[136:139], v[184:187], v[72:75]
	v_mfma_f32_16x16x32_bf16 v[124:127], v[132:135], v[164:167], v[124:127]
	v_mfma_f32_16x16x32_bf16 v[120:123], v[140:143], v[164:167], v[120:123]
	v_mfma_f32_16x16x32_bf16 v[116:119], v[132:135], v[172:175], v[116:119]
	v_mfma_f32_16x16x32_bf16 v[112:115], v[140:143], v[172:175], v[112:115]
	v_mfma_f32_16x16x32_bf16 v[108:111], v[132:135], v[180:183], v[108:111]
	v_mfma_f32_16x16x32_bf16 v[100:103], v[140:143], v[180:183], v[100:103]
	v_mfma_f32_16x16x32_bf16 v[80:83], v[132:135], v[188:191], v[80:83]
	v_mfma_f32_16x16x32_bf16 v[72:75], v[140:143], v[188:191], v[72:75]
	v_mfma_f32_16x16x32_bf16 v[104:107], v[144:147], v[160:163], v[104:107]
	v_mfma_f32_16x16x32_bf16 v[96:99], v[152:155], v[160:163], v[96:99]
	v_mfma_f32_16x16x32_bf16 v[92:95], v[144:147], v[168:171], v[92:95]
	v_mfma_f32_16x16x32_bf16 v[88:91], v[152:155], v[168:171], v[88:91]
	v_mfma_f32_16x16x32_bf16 v[84:87], v[144:147], v[176:179], v[84:87]
	v_mfma_f32_16x16x32_bf16 v[76:79], v[152:155], v[176:179], v[76:79]
	v_mfma_f32_16x16x32_bf16 v[68:71], v[144:147], v[184:187], v[68:71]
	v_mfma_f32_16x16x32_bf16 v[64:67], v[152:155], v[184:187], v[64:67]
	v_mfma_f32_16x16x32_bf16 v[104:107], v[148:151], v[164:167], v[104:107]
	v_mfma_f32_16x16x32_bf16 v[96:99], v[156:159], v[164:167], v[96:99]
	v_mfma_f32_16x16x32_bf16 v[92:95], v[148:151], v[172:175], v[92:95]
	v_mfma_f32_16x16x32_bf16 v[88:91], v[156:159], v[172:175], v[88:91]
	v_mfma_f32_16x16x32_bf16 v[84:87], v[148:151], v[180:183], v[84:87]
	v_mfma_f32_16x16x32_bf16 v[76:79], v[156:159], v[180:183], v[76:79]
	v_mfma_f32_16x16x32_bf16 v[68:71], v[148:151], v[188:191], v[68:71]
	v_mfma_f32_16x16x32_bf16 v[64:67], v[156:159], v[188:191], v[64:67]
	s_barrier
	s_add_i32 s20, s45, s26
	v_lshl_add_u64 v[192:193], v[192:193], 0, s[14:15]
	s_mov_b32 m0, s20
	ds_read_b128 v[160:163], v242 offset:49152
	ds_read_b128 v[164:167], v242 offset:50176
	ds_read_b128 v[168:171], v242 offset:51200
	ds_read_b128 v[172:175], v242 offset:52224
	ds_read_b128 v[176:179], v242 offset:53248
	ds_read_b128 v[180:183], v242 offset:54272
	ds_read_b128 v[184:187], v242 offset:55296
	ds_read_b128 v[188:191], v242 offset:56320
	global_load_lds_dwordx4 v[192:193], off
	s_add_i32 m0, s20, 0x2000
	s_add_u32 s18, s18, 0xb0080
	v_lshl_add_u64 v[192:193], v[194:195], 0, s[14:15]
	s_addc_u32 s19, s19, 0
	s_add_i32 s20, s46, s26
	global_load_lds_dwordx4 v[192:193], off
	v_lshl_add_u64 v[192:193], s[18:19], 0, v[212:213]
	s_mov_b32 m0, s20
	s_nop 0
	global_load_lds_dwordx4 v[192:193], off
	v_lshl_add_u64 v[192:193], s[18:19], 0, v[216:217]
	s_add_i32 m0, s20, 0x2000
	s_nop 0
	global_load_lds_dwordx4 v[192:193], off
	v_lshl_add_u64 v[192:193], v[196:197], 0, s[14:15]
	s_mov_b32 m0, s33
	s_nop 0
	global_load_lds_dwordx4 v[192:193], off
	v_lshl_add_u64 v[192:193], v[198:199], 0, s[14:15]
	s_mov_b32 m0, s34
	s_nop 0
	global_load_lds_dwordx4 v[192:193], off
	s_waitcnt vmcnt(8)
	s_waitcnt lgkmcnt(0)
	s_barrier
	s_waitcnt lgkmcnt(0)
	v_mfma_f32_16x16x32_bf16 v[60:63], v[128:131], v[160:163], v[60:63]
	v_mfma_f32_16x16x32_bf16 v[56:59], v[136:139], v[160:163], v[56:59]
	v_mfma_f32_16x16x32_bf16 v[52:55], v[128:131], v[168:171], v[52:55]
	v_mfma_f32_16x16x32_bf16 v[48:51], v[136:139], v[168:171], v[48:51]
	v_mfma_f32_16x16x32_bf16 v[44:47], v[128:131], v[176:179], v[44:47]
	v_mfma_f32_16x16x32_bf16 v[36:39], v[136:139], v[176:179], v[36:39]
	v_mfma_f32_16x16x32_bf16 v[20:23], v[128:131], v[184:187], v[20:23]
	v_mfma_f32_16x16x32_bf16 v[12:15], v[136:139], v[184:187], v[12:15]
	v_mfma_f32_16x16x32_bf16 v[60:63], v[132:135], v[164:167], v[60:63]
	v_mfma_f32_16x16x32_bf16 v[56:59], v[140:143], v[164:167], v[56:59]
	v_mfma_f32_16x16x32_bf16 v[52:55], v[132:135], v[172:175], v[52:55]
	v_mfma_f32_16x16x32_bf16 v[48:51], v[140:143], v[172:175], v[48:51]
	v_mfma_f32_16x16x32_bf16 v[44:47], v[132:135], v[180:183], v[44:47]
	v_mfma_f32_16x16x32_bf16 v[36:39], v[140:143], v[180:183], v[36:39]
	v_mfma_f32_16x16x32_bf16 v[20:23], v[132:135], v[188:191], v[20:23]
	v_mfma_f32_16x16x32_bf16 v[12:15], v[140:143], v[188:191], v[12:15]
	v_mfma_f32_16x16x32_bf16 v[40:43], v[144:147], v[160:163], v[40:43]
	v_mfma_f32_16x16x32_bf16 v[32:35], v[152:155], v[160:163], v[32:35]
	v_mfma_f32_16x16x32_bf16 v[28:31], v[144:147], v[168:171], v[28:31]
	v_mfma_f32_16x16x32_bf16 v[24:27], v[152:155], v[168:171], v[24:27]
	v_mfma_f32_16x16x32_bf16 v[16:19], v[144:147], v[176:179], v[16:19]
	v_mfma_f32_16x16x32_bf16 v[8:11], v[152:155], v[176:179], v[8:11]
	v_mfma_f32_16x16x32_bf16 v[4:7], v[144:147], v[184:187], v[4:7]
	v_mfma_f32_16x16x32_bf16 v[0:3], v[152:155], v[184:187], v[0:3]
	v_mfma_f32_16x16x32_bf16 v[40:43], v[148:151], v[164:167], v[40:43]
	v_mfma_f32_16x16x32_bf16 v[32:35], v[156:159], v[164:167], v[32:35]
	v_mfma_f32_16x16x32_bf16 v[28:31], v[148:151], v[172:175], v[28:31]
	v_mfma_f32_16x16x32_bf16 v[24:27], v[156:159], v[172:175], v[24:27]
	v_mfma_f32_16x16x32_bf16 v[16:19], v[148:151], v[180:183], v[16:19]
	v_mfma_f32_16x16x32_bf16 v[8:11], v[156:159], v[180:183], v[8:11]
	v_mfma_f32_16x16x32_bf16 v[4:7], v[148:151], v[188:191], v[4:7]
	v_mfma_f32_16x16x32_bf16 v[0:3], v[156:159], v[188:191], v[0:3]
	s_barrier
	s_add_i32 s44, s44, 2
	s_add_u32 s4, s4, 0x100
	s_addc_u32 s5, s5, 0
	s_add_u32 s42, s42, 0x100
	s_addc_u32 s43, s43, 0
	s_cmp_gt_u32 s44, 41
	s_cbranch_scc0 .LBB0_324
	s_cmp_gt_i32 s22, 63
	s_cselect_b64 s[18:19], -1, 0
	s_lshl_b32 s4, s22, 2
	s_add_i32 s43, s35, s4
	s_ashr_i32 s42, s22, 3
	s_cmp_lt_i32 s22, 64
	s_cselect_b64 s[4:5], -1, 0
	s_and_b64 vcc, s[4:5], exec
	s_cselect_b32 s20, s42, s43
	v_readlane_b32 s44, v246, 21
	v_lshl_or_b32 v128, s23, 8, v239
	v_lshl_add_u32 v228, s22, 8, v237
	s_mul_i32 s22, s20, 0x9000
	v_readlane_b32 s45, v246, 22
	v_readlane_b32 s46, v246, 23
	v_readlane_b32 s47, v246, 24
	v_ashrrev_i32_e32 v129, 31, v128
	v_add_u32_e32 v130, 0xffffc000, v228
	s_mul_hi_i32 s23, s20, 0x9000
	s_cselect_b32 s21, s45, s47
	s_cselect_b32 s20, s44, s46
	s_add_u32 s22, s10, s22
	v_or_b32_e32 v230, 16, v228
	v_add_u32_e32 v140, 0xffffc010, v228
	v_or_b32_e32 v232, 32, v228
	v_add_u32_e32 v156, 0xffffc020, v228
	v_cndmask_b32_e64 v130, v130, v228, s[4:5]
	s_addc_u32 s23, s11, s23
	v_lshlrev_b64 v[226:227], 2, v[128:129]
	v_cndmask_b32_e64 v140, v140, v230, s[4:5]
	v_cndmask_b32_e64 v156, v156, v232, s[4:5]
	v_lshl_add_u64 v[128:129], s[22:23], 0, v[226:227]
	v_ashrrev_i32_e32 v131, 31, v130
	v_ashrrev_i32_e32 v141, 31, v140
	v_ashrrev_i32_e32 v157, 31, v156
	global_load_dwordx4 v[196:199], v[128:129], off offset:16
	global_load_dwordx4 v[204:207], v[128:129], off
	global_load_dwordx4 v[192:195], v[128:129], off offset:528
	global_load_dwordx4 v[200:203], v[128:129], off offset:512
	v_lshlrev_b64 v[128:129], 12, v[130:131]
	v_lshlrev_b64 v[140:141], 12, v[140:141]
	v_lshlrev_b64 v[156:157], 12, v[156:157]
	v_lshl_add_u64 v[128:129], s[20:21], 0, v[128:129]
	v_lshl_add_u64 v[140:141], s[20:21], 0, v[140:141]
	v_lshl_add_u64 v[156:157], s[20:21], 0, v[156:157]
	v_lshl_add_u64 v[136:137], v[128:129], 0, v[226:227]
	v_lshl_add_u64 v[152:153], v[140:141], 0, v[226:227]
	v_lshl_add_u64 v[168:169], v[156:157], 0, v[226:227]
	global_load_dwordx4 v[132:135], v[136:137], off offset:16 nt
	global_load_dwordx4 v[144:147], v[136:137], off nt
	global_load_dwordx4 v[128:131], v[136:137], off offset:528 nt
	s_nop 0
	global_load_dwordx4 v[136:139], v[136:137], off offset:512 nt
	s_nop 0
	global_load_dwordx4 v[148:151], v[152:153], off offset:16 nt
	global_load_dwordx4 v[160:163], v[152:153], off nt
	global_load_dwordx4 v[140:143], v[152:153], off offset:528 nt
	s_nop 0
	global_load_dwordx4 v[152:155], v[152:153], off offset:512 nt
	s_nop 0
	global_load_dwordx4 v[164:167], v[168:169], off offset:16 nt
	global_load_dwordx4 v[172:175], v[168:169], off nt
	global_load_dwordx4 v[156:159], v[168:169], off offset:528 nt
	s_nop 0
	global_load_dwordx4 v[168:171], v[168:169], off offset:512 nt
	v_or_b32_e32 v178, 48, v228
	s_mov_b64 s[22:23], -1
	v_ashrrev_i32_e32 v179, 31, v178
	v_readlane_b32 s48, v246, 25
	v_readlane_b32 s49, v246, 26
	v_readlane_b32 s50, v246, 27
	v_readlane_b32 s51, v246, 28
	v_readlane_b32 s52, v246, 29
	v_readlane_b32 s53, v246, 30
	v_readlane_b32 s54, v246, 31
	v_readlane_b32 s55, v246, 32
	v_readlane_b32 s56, v246, 33
	v_readlane_b32 s57, v246, 34
	v_readlane_b32 s58, v246, 35
	v_readlane_b32 s59, v246, 36
	s_cbranch_vccnz .LBB0_327
	v_add_u32_e32 v176, 0xffffc030, v228
	v_ashrrev_i32_e32 v177, 31, v176
	v_readlane_b32 s44, v246, 21
	v_lshlrev_b64 v[176:177], 12, v[176:177]
	v_readlane_b32 s46, v246, 23
	v_readlane_b32 s47, v246, 24
	v_lshlrev_b64 v[234:235], 12, v[178:179]
	s_mov_b64 s[22:23], 0
	v_lshl_add_u64 v[176:177], s[46:47], 0, v[176:177]
	v_readlane_b32 s45, v246, 22
	v_readlane_b32 s48, v246, 25
	v_readlane_b32 s49, v246, 26
	v_readlane_b32 s50, v246, 27
	v_readlane_b32 s51, v246, 28
	v_readlane_b32 s52, v246, 29
	v_readlane_b32 s53, v246, 30
	v_readlane_b32 s54, v246, 31
	v_readlane_b32 s55, v246, 32
	v_readlane_b32 s56, v246, 33
	v_readlane_b32 s57, v246, 34
	v_readlane_b32 s58, v246, 35
	v_readlane_b32 s59, v246, 36

.LBB0_524:
	ds_read_b128 v[128:131], v166
	ds_read_b128 v[132:135], v166 offset:1024
	ds_read_b128 v[156:159], v166 offset:2048
	ds_read_b128 v[172:175], v166 offset:3072
	ds_read_b128 v[176:179], v167
	ds_read_b128 v[180:183], v167 offset:1024
	ds_read_b128 v[184:187], v167 offset:2048
	ds_read_b128 v[188:191], v167 offset:3072
	s_add_u32 s26, s4, 0xfffc0080
	s_addc_u32 s27, s5, -1
	s_cmp_eq_u32 s53, 12
	s_cselect_b32 s29, s7, s27
	s_cselect_b32 s28, s9, s26
	s_cselect_b32 s27, s19, s31
	s_cselect_b32 s26, s21, s30
	v_lshl_add_u64 v[160:161], s[4:5], 0, v[148:149]
	s_add_i32 m0, s36, 0xc000
	ds_read_b128 v[192:195], v168
	ds_read_b128 v[196:199], v168 offset:1024
	ds_read_b128 v[200:203], v168 offset:2048
	ds_read_b128 v[204:207], v168 offset:3072
	ds_read_b128 v[210:213], v168 offset:4096
	ds_read_b128 v[214:217], v168 offset:5120
	ds_read_b128 v[218:221], v168 offset:6144
	ds_read_b128 v[222:225], v168 offset:7168
	global_load_lds_dwordx4 v[160:161], off
	v_lshl_add_u64 v[160:161], s[4:5], 0, v[150:151]
	s_add_i32 m0, s36, 0xe000
	s_nop 0
	global_load_lds_dwordx4 v[160:161], off
	s_waitcnt vmcnt(8)
	s_waitcnt lgkmcnt(0)
	s_barrier
	s_waitcnt lgkmcnt(0)
	v_mfma_f32_16x16x32_bf16 v[124:127], v[128:131], v[192:195], v[124:127]
	v_mfma_f32_16x16x32_bf16 v[120:123], v[156:159], v[192:195], v[120:123]
	v_mfma_f32_16x16x32_bf16 v[108:111], v[128:131], v[200:203], v[108:111]
	v_mfma_f32_16x16x32_bf16 v[104:107], v[156:159], v[200:203], v[104:107]
	v_mfma_f32_16x16x32_bf16 v[92:95], v[128:131], v[210:213], v[92:95]
	v_mfma_f32_16x16x32_bf16 v[88:91], v[156:159], v[210:213], v[88:91]
	v_mfma_f32_16x16x32_bf16 v[76:79], v[128:131], v[218:221], v[76:79]
	v_mfma_f32_16x16x32_bf16 v[72:75], v[156:159], v[218:221], v[72:75]
	v_mfma_f32_16x16x32_bf16 v[124:127], v[132:135], v[196:199], v[124:127]
	v_mfma_f32_16x16x32_bf16 v[120:123], v[172:175], v[196:199], v[120:123]
	v_mfma_f32_16x16x32_bf16 v[108:111], v[132:135], v[204:207], v[108:111]
	v_mfma_f32_16x16x32_bf16 v[104:107], v[172:175], v[204:207], v[104:107]
	v_mfma_f32_16x16x32_bf16 v[92:95], v[132:135], v[214:217], v[92:95]
	v_mfma_f32_16x16x32_bf16 v[88:91], v[172:175], v[214:217], v[88:91]
	v_mfma_f32_16x16x32_bf16 v[76:79], v[132:135], v[222:225], v[76:79]
	v_mfma_f32_16x16x32_bf16 v[72:75], v[172:175], v[222:225], v[72:75]
	v_mfma_f32_16x16x32_bf16 v[116:119], v[176:179], v[192:195], v[116:119]
	v_mfma_f32_16x16x32_bf16 v[112:115], v[184:187], v[192:195], v[112:115]
	v_mfma_f32_16x16x32_bf16 v[100:103], v[176:179], v[200:203], v[100:103]
	v_mfma_f32_16x16x32_bf16 v[96:99], v[184:187], v[200:203], v[96:99]
	v_mfma_f32_16x16x32_bf16 v[84:87], v[176:179], v[210:213], v[84:87]
	v_mfma_f32_16x16x32_bf16 v[80:83], v[184:187], v[210:213], v[80:83]
	v_mfma_f32_16x16x32_bf16 v[68:71], v[176:179], v[218:221], v[68:71]
	v_mfma_f32_16x16x32_bf16 v[64:67], v[184:187], v[218:221], v[64:67]
	v_mfma_f32_16x16x32_bf16 v[116:119], v[180:183], v[196:199], v[116:119]
	v_mfma_f32_16x16x32_bf16 v[112:115], v[188:191], v[196:199], v[112:115]
	v_mfma_f32_16x16x32_bf16 v[100:103], v[180:183], v[204:207], v[100:103]
	v_mfma_f32_16x16x32_bf16 v[96:99], v[188:191], v[204:207], v[96:99]
	v_mfma_f32_16x16x32_bf16 v[84:87], v[180:183], v[214:217], v[84:87]
	v_mfma_f32_16x16x32_bf16 v[80:83], v[188:191], v[214:217], v[80:83]
	v_mfma_f32_16x16x32_bf16 v[68:71], v[180:183], v[222:225], v[68:71]
	v_mfma_f32_16x16x32_bf16 v[64:67], v[188:191], v[222:225], v[64:67]
	s_barrier
	s_add_i32 s54, s47, s35
	v_lshl_add_u64 v[160:161], s[26:27], 0, v[138:139]
	s_mov_b32 m0, s54
	ds_read_b128 v[192:195], v168 offset:16384
	ds_read_b128 v[196:199], v168 offset:17408
	ds_read_b128 v[200:203], v168 offset:18432
	ds_read_b128 v[204:207], v168 offset:19456
	ds_read_b128 v[210:213], v168 offset:20480
	ds_read_b128 v[214:217], v168 offset:21504
	ds_read_b128 v[218:221], v168 offset:22528
	ds_read_b128 v[222:225], v168 offset:23552
	global_load_lds_dwordx4 v[160:161], off
	s_add_i32 m0, s54, 0x2000
	s_add_u32 s54, s26, 0x40000
	v_lshl_add_u64 v[226:227], s[26:27], 0, v[142:143]
	s_addc_u32 s55, s27, 0
	s_add_i32 s56, s48, s35
	global_load_lds_dwordx4 v[226:227], off
	v_lshl_add_u64 v[228:229], s[54:55], 0, v[138:139]
	s_mov_b32 m0, s56
	v_lshl_add_u64 v[230:231], s[28:29], 0, v[140:141]
	global_load_lds_dwordx4 v[228:229], off
	v_lshl_add_u64 v[228:229], s[54:55], 0, v[142:143]
	s_add_i32 m0, s56, 0x2000
	s_nop 0
	global_load_lds_dwordx4 v[228:229], off
	v_lshl_add_u64 v[228:229], s[28:29], 0, v[136:137]
	s_mov_b32 m0, s36
	s_nop 0
	global_load_lds_dwordx4 v[228:229], off
	s_mov_b32 m0, s37
	s_nop 0
	global_load_lds_dwordx4 v[230:231], off
	s_waitcnt vmcnt(8)
	s_waitcnt lgkmcnt(0)
	s_barrier
	s_waitcnt lgkmcnt(0)
	v_mfma_f32_16x16x32_bf16 v[60:63], v[128:131], v[192:195], v[60:63]
	v_mfma_f32_16x16x32_bf16 v[56:59], v[156:159], v[192:195], v[56:59]
	v_mfma_f32_16x16x32_bf16 v[44:47], v[128:131], v[200:203], v[44:47]
	v_mfma_f32_16x16x32_bf16 v[40:43], v[156:159], v[200:203], v[40:43]
	v_mfma_f32_16x16x32_bf16 v[28:31], v[128:131], v[210:213], v[28:31]
	v_mfma_f32_16x16x32_bf16 v[24:27], v[156:159], v[210:213], v[24:27]
	v_mfma_f32_16x16x32_bf16 v[12:15], v[128:131], v[218:221], v[12:15]
	v_mfma_f32_16x16x32_bf16 v[8:11], v[156:159], v[218:221], v[8:11]
	v_mfma_f32_16x16x32_bf16 v[60:63], v[132:135], v[196:199], v[60:63]
	v_mfma_f32_16x16x32_bf16 v[56:59], v[172:175], v[196:199], v[56:59]
	v_mfma_f32_16x16x32_bf16 v[44:47], v[132:135], v[204:207], v[44:47]
	v_mfma_f32_16x16x32_bf16 v[40:43], v[172:175], v[204:207], v[40:43]
	v_mfma_f32_16x16x32_bf16 v[28:31], v[132:135], v[214:217], v[28:31]
	v_mfma_f32_16x16x32_bf16 v[24:27], v[172:175], v[214:217], v[24:27]
	v_mfma_f32_16x16x32_bf16 v[12:15], v[132:135], v[222:225], v[12:15]
	v_mfma_f32_16x16x32_bf16 v[8:11], v[172:175], v[222:225], v[8:11]
	v_mfma_f32_16x16x32_bf16 v[52:55], v[176:179], v[192:195], v[52:55]
	v_mfma_f32_16x16x32_bf16 v[48:51], v[184:187], v[192:195], v[48:51]
	v_mfma_f32_16x16x32_bf16 v[36:39], v[176:179], v[200:203], v[36:39]
	v_mfma_f32_16x16x32_bf16 v[32:35], v[184:187], v[200:203], v[32:35]
	v_mfma_f32_16x16x32_bf16 v[20:23], v[176:179], v[210:213], v[20:23]
	v_mfma_f32_16x16x32_bf16 v[16:19], v[184:187], v[210:213], v[16:19]
	v_mfma_f32_16x16x32_bf16 v[4:7], v[176:179], v[218:221], v[4:7]
	v_mfma_f32_16x16x32_bf16 v[0:3], v[184:187], v[218:221], v[0:3]
	v_mfma_f32_16x16x32_bf16 v[52:55], v[180:183], v[196:199], v[52:55]
	v_mfma_f32_16x16x32_bf16 v[48:51], v[188:191], v[196:199], v[48:51]
	v_mfma_f32_16x16x32_bf16 v[36:39], v[180:183], v[204:207], v[36:39]
	v_mfma_f32_16x16x32_bf16 v[32:35], v[188:191], v[204:207], v[32:35]
	v_mfma_f32_16x16x32_bf16 v[20:23], v[180:183], v[214:217], v[20:23]
	v_mfma_f32_16x16x32_bf16 v[16:19], v[188:191], v[214:217], v[16:19]
	v_mfma_f32_16x16x32_bf16 v[4:7], v[180:183], v[222:225], v[4:7]
	v_mfma_f32_16x16x32_bf16 v[0:3], v[188:191], v[222:225], v[0:3]
	s_barrier
	s_add_i32 s54, 0, 0x18000
	v_add_u32_e32 v144, s54, v164
	s_add_i32 s55, 0, 0x1c000
	ds_read_b128 v[128:131], v144
	ds_read_b128 v[132:135], v144 offset:1024
	ds_read_b128 v[156:159], v144 offset:2048
	ds_read_b128 v[172:175], v144 offset:3072
	v_add_u32_e32 v144, s55, v164
	ds_read_b128 v[176:179], v144
	ds_read_b128 v[180:183], v144 offset:1024
	ds_read_b128 v[184:187], v144 offset:2048
	ds_read_b128 v[188:191], v144 offset:3072
	s_add_u32 s28, s28, 0x40000
	s_addc_u32 s29, s29, 0
	s_mov_b32 m0, s38
	v_lshl_add_u64 v[232:233], s[28:29], 0, v[136:137]
	ds_read_b128 v[192:195], v168 offset:32768
	ds_read_b128 v[196:199], v168 offset:33792
	ds_read_b128 v[200:203], v168 offset:34816
	ds_read_b128 v[204:207], v168 offset:35840
	ds_read_b128 v[210:213], v168 offset:36864
	ds_read_b128 v[214:217], v168 offset:37888
	ds_read_b128 v[218:221], v168 offset:38912
	ds_read_b128 v[222:225], v168 offset:39936
	global_load_lds_dwordx4 v[232:233], off
	v_lshl_add_u64 v[232:233], s[28:29], 0, v[140:141]
	s_mov_b32 m0, s39
	s_nop 0
	global_load_lds_dwordx4 v[232:233], off
	s_waitcnt vmcnt(8)
	s_waitcnt lgkmcnt(0)
	s_barrier
	s_waitcnt lgkmcnt(0)
	v_mfma_f32_16x16x32_bf16 v[124:127], v[128:131], v[192:195], v[124:127]
	v_mfma_f32_16x16x32_bf16 v[120:123], v[156:159], v[192:195], v[120:123]
	v_mfma_f32_16x16x32_bf16 v[108:111], v[128:131], v[200:203], v[108:111]
	v_mfma_f32_16x16x32_bf16 v[104:107], v[156:159], v[200:203], v[104:107]
	v_mfma_f32_16x16x32_bf16 v[92:95], v[128:131], v[210:213], v[92:95]
	v_mfma_f32_16x16x32_bf16 v[88:91], v[156:159], v[210:213], v[88:91]
	v_mfma_f32_16x16x32_bf16 v[76:79], v[128:131], v[218:221], v[76:79]
	v_mfma_f32_16x16x32_bf16 v[72:75], v[156:159], v[218:221], v[72:75]
	v_mfma_f32_16x16x32_bf16 v[124:127], v[132:135], v[196:199], v[124:127]
	v_mfma_f32_16x16x32_bf16 v[120:123], v[172:175], v[196:199], v[120:123]
	v_mfma_f32_16x16x32_bf16 v[108:111], v[132:135], v[204:207], v[108:111]
	v_mfma_f32_16x16x32_bf16 v[104:107], v[172:175], v[204:207], v[104:107]
	v_mfma_f32_16x16x32_bf16 v[92:95], v[132:135], v[214:217], v[92:95]
	v_mfma_f32_16x16x32_bf16 v[88:91], v[172:175], v[214:217], v[88:91]
	v_mfma_f32_16x16x32_bf16 v[76:79], v[132:135], v[222:225], v[76:79]
	v_mfma_f32_16x16x32_bf16 v[72:75], v[172:175], v[222:225], v[72:75]
	v_mfma_f32_16x16x32_bf16 v[116:119], v[176:179], v[192:195], v[116:119]
	v_mfma_f32_16x16x32_bf16 v[112:115], v[184:187], v[192:195], v[112:115]
	v_mfma_f32_16x16x32_bf16 v[100:103], v[176:179], v[200:203], v[100:103]
	v_mfma_f32_16x16x32_bf16 v[96:99], v[184:187], v[200:203], v[96:99]
	v_mfma_f32_16x16x32_bf16 v[84:87], v[176:179], v[210:213], v[84:87]
	v_mfma_f32_16x16x32_bf16 v[80:83], v[184:187], v[210:213], v[80:83]
	v_mfma_f32_16x16x32_bf16 v[68:71], v[176:179], v[218:221], v[68:71]
	v_mfma_f32_16x16x32_bf16 v[64:67], v[184:187], v[218:221], v[64:67]
	v_mfma_f32_16x16x32_bf16 v[116:119], v[180:183], v[196:199], v[116:119]
	v_mfma_f32_16x16x32_bf16 v[112:115], v[188:191], v[196:199], v[112:115]
	v_mfma_f32_16x16x32_bf16 v[100:103], v[180:183], v[204:207], v[100:103]
	v_mfma_f32_16x16x32_bf16 v[96:99], v[188:191], v[204:207], v[96:99]
	v_mfma_f32_16x16x32_bf16 v[84:87], v[180:183], v[214:217], v[84:87]
	v_mfma_f32_16x16x32_bf16 v[80:83], v[188:191], v[214:217], v[80:83]
	v_mfma_f32_16x16x32_bf16 v[68:71], v[180:183], v[222:225], v[68:71]
	v_mfma_f32_16x16x32_bf16 v[64:67], v[188:191], v[222:225], v[64:67]
	s_barrier
	s_add_i32 s28, s54, s35
	v_lshl_add_u64 v[160:161], v[160:161], 0, s[12:13]
	s_mov_b32 m0, s28
	ds_read_b128 v[192:195], v168 offset:49152
	ds_read_b128 v[196:199], v168 offset:50176
	ds_read_b128 v[200:203], v168 offset:51200
	ds_read_b128 v[204:207], v168 offset:52224
	ds_read_b128 v[210:213], v168 offset:53248
	ds_read_b128 v[214:217], v168 offset:54272
	ds_read_b128 v[218:221], v168 offset:55296
	ds_read_b128 v[222:225], v168 offset:56320
	global_load_lds_dwordx4 v[160:161], off
	s_add_i32 m0, s28, 0x2000
	s_add_u32 s26, s26, 0x40080
	v_lshl_add_u64 v[160:161], v[226:227], 0, s[12:13]
	s_addc_u32 s27, s27, 0
	s_add_i32 s28, s55, s35
	global_load_lds_dwordx4 v[160:161], off
	v_lshl_add_u64 v[160:161], s[26:27], 0, v[138:139]
	s_mov_b32 m0, s28
	s_nop 0
	global_load_lds_dwordx4 v[160:161], off
	v_lshl_add_u64 v[160:161], s[26:27], 0, v[142:143]
	s_add_i32 m0, s28, 0x2000
	s_nop 0
	global_load_lds_dwordx4 v[160:161], off
	v_lshl_add_u64 v[160:161], v[228:229], 0, s[12:13]
	s_mov_b32 m0, s42
	s_nop 0
	global_load_lds_dwordx4 v[160:161], off
	v_lshl_add_u64 v[160:161], v[230:231], 0, s[12:13]
	s_mov_b32 m0, s43
	s_nop 0
	global_load_lds_dwordx4 v[160:161], off
	s_waitcnt vmcnt(8)
	s_waitcnt lgkmcnt(0)
	s_barrier
	s_waitcnt lgkmcnt(0)
	v_mfma_f32_16x16x32_bf16 v[60:63], v[128:131], v[192:195], v[60:63]
	v_mfma_f32_16x16x32_bf16 v[56:59], v[156:159], v[192:195], v[56:59]
	v_mfma_f32_16x16x32_bf16 v[44:47], v[128:131], v[200:203], v[44:47]
	v_mfma_f32_16x16x32_bf16 v[40:43], v[156:159], v[200:203], v[40:43]
	v_mfma_f32_16x16x32_bf16 v[28:31], v[128:131], v[210:213], v[28:31]
	v_mfma_f32_16x16x32_bf16 v[24:27], v[156:159], v[210:213], v[24:27]
	v_mfma_f32_16x16x32_bf16 v[12:15], v[128:131], v[218:221], v[12:15]
	v_mfma_f32_16x16x32_bf16 v[8:11], v[156:159], v[218:221], v[8:11]
	v_mfma_f32_16x16x32_bf16 v[60:63], v[132:135], v[196:199], v[60:63]
	v_mfma_f32_16x16x32_bf16 v[56:59], v[172:175], v[196:199], v[56:59]
	v_mfma_f32_16x16x32_bf16 v[44:47], v[132:135], v[204:207], v[44:47]
	v_mfma_f32_16x16x32_bf16 v[40:43], v[172:175], v[204:207], v[40:43]
	v_mfma_f32_16x16x32_bf16 v[28:31], v[132:135], v[214:217], v[28:31]
	v_mfma_f32_16x16x32_bf16 v[24:27], v[172:175], v[214:217], v[24:27]
	v_mfma_f32_16x16x32_bf16 v[12:15], v[132:135], v[222:225], v[12:15]
	v_mfma_f32_16x16x32_bf16 v[8:11], v[172:175], v[222:225], v[8:11]
	v_mfma_f32_16x16x32_bf16 v[52:55], v[176:179], v[192:195], v[52:55]
	v_mfma_f32_16x16x32_bf16 v[48:51], v[184:187], v[192:195], v[48:51]
	v_mfma_f32_16x16x32_bf16 v[36:39], v[176:179], v[200:203], v[36:39]
	v_mfma_f32_16x16x32_bf16 v[32:35], v[184:187], v[200:203], v[32:35]
	v_mfma_f32_16x16x32_bf16 v[20:23], v[176:179], v[210:213], v[20:23]
	v_mfma_f32_16x16x32_bf16 v[16:19], v[184:187], v[210:213], v[16:19]
	v_mfma_f32_16x16x32_bf16 v[4:7], v[176:179], v[218:221], v[4:7]
	v_mfma_f32_16x16x32_bf16 v[0:3], v[184:187], v[218:221], v[0:3]
	v_mfma_f32_16x16x32_bf16 v[52:55], v[180:183], v[196:199], v[52:55]
	v_mfma_f32_16x16x32_bf16 v[48:51], v[188:191], v[196:199], v[48:51]
	v_mfma_f32_16x16x32_bf16 v[36:39], v[180:183], v[204:207], v[36:39]
	v_mfma_f32_16x16x32_bf16 v[32:35], v[188:191], v[204:207], v[32:35]
	v_mfma_f32_16x16x32_bf16 v[20:23], v[180:183], v[214:217], v[20:23]
	v_mfma_f32_16x16x32_bf16 v[16:19], v[188:191], v[214:217], v[16:19]
	v_mfma_f32_16x16x32_bf16 v[4:7], v[180:183], v[222:225], v[4:7]
	v_mfma_f32_16x16x32_bf16 v[0:3], v[188:191], v[222:225], v[0:3]
	s_barrier
	s_add_i32 s53, s53, 2
	s_add_u32 s4, s4, 0x100
	s_addc_u32 s5, s5, 0
	s_add_u32 s30, s30, 0x100
	s_addc_u32 s31, s31, 0
	s_cmp_gt_u32 s53, 13
	s_cbranch_scc0 .LBB0_524
	s_and_b64 vcc, exec, s[14:15]
	s_cbranch_vccz .LBB0_527
	s_barrier

.LBB0_1028:
	ds_read_b128 v[128:131], v240
	ds_read_b128 v[132:135], v240 offset:1024
	ds_read_b128 v[136:139], v240 offset:2048
	ds_read_b128 v[140:143], v240 offset:3072
	ds_read_b128 v[144:147], v241
	ds_read_b128 v[148:151], v241 offset:1024
	ds_read_b128 v[152:155], v241 offset:2048
	ds_read_b128 v[156:159], v241 offset:3072
	s_add_u32 s24, s22, 0xfffc0080
	s_addc_u32 s25, s23, -1
	s_cmp_eq_u32 s50, 12
	s_cselect_b32 s27, s17, s25
	s_cselect_b32 s26, s46, s24
	s_cselect_b32 s25, s15, s49
	s_cselect_b32 s24, s47, s48
	v_lshl_add_u64 v[192:193], s[22:23], 0, v[218:219]
	s_add_i32 m0, s34, 0xc000
	ds_read_b128 v[160:163], v242
	ds_read_b128 v[164:167], v242 offset:1024
	ds_read_b128 v[168:171], v242 offset:2048
	ds_read_b128 v[172:175], v242 offset:3072
	ds_read_b128 v[176:179], v242 offset:4096
	ds_read_b128 v[180:183], v242 offset:5120
	ds_read_b128 v[184:187], v242 offset:6144
	ds_read_b128 v[188:191], v242 offset:7168
	global_load_lds_dwordx4 v[192:193], off
	v_lshl_add_u64 v[192:193], s[22:23], 0, v[220:221]
	s_add_i32 m0, s34, 0xe000
	s_nop 0
	global_load_lds_dwordx4 v[192:193], off
	s_waitcnt vmcnt(8)
	s_waitcnt lgkmcnt(0)
	s_barrier
	s_waitcnt lgkmcnt(0)
	v_mfma_f32_16x16x32_bf16 v[124:127], v[128:131], v[160:163], v[124:127]
	v_mfma_f32_16x16x32_bf16 v[120:123], v[136:139], v[160:163], v[120:123]
	v_mfma_f32_16x16x32_bf16 v[112:115], v[128:131], v[168:171], v[112:115]
	v_mfma_f32_16x16x32_bf16 v[104:107], v[136:139], v[168:171], v[104:107]
	v_mfma_f32_16x16x32_bf16 v[96:99], v[128:131], v[176:179], v[96:99]
	v_mfma_f32_16x16x32_bf16 v[88:91], v[136:139], v[176:179], v[88:91]
	v_mfma_f32_16x16x32_bf16 v[76:79], v[128:131], v[184:187], v[76:79]
	v_mfma_f32_16x16x32_bf16 v[72:75], v[136:139], v[184:187], v[72:75]
	v_mfma_f32_16x16x32_bf16 v[124:127], v[132:135], v[164:167], v[124:127]
	v_mfma_f32_16x16x32_bf16 v[120:123], v[140:143], v[164:167], v[120:123]
	v_mfma_f32_16x16x32_bf16 v[112:115], v[132:135], v[172:175], v[112:115]
	v_mfma_f32_16x16x32_bf16 v[104:107], v[140:143], v[172:175], v[104:107]
	v_mfma_f32_16x16x32_bf16 v[96:99], v[132:135], v[180:183], v[96:99]
	v_mfma_f32_16x16x32_bf16 v[88:91], v[140:143], v[180:183], v[88:91]
	v_mfma_f32_16x16x32_bf16 v[76:79], v[132:135], v[188:191], v[76:79]
	v_mfma_f32_16x16x32_bf16 v[72:75], v[140:143], v[188:191], v[72:75]
	v_mfma_f32_16x16x32_bf16 v[116:119], v[144:147], v[160:163], v[116:119]
	v_mfma_f32_16x16x32_bf16 v[108:111], v[152:155], v[160:163], v[108:111]
	v_mfma_f32_16x16x32_bf16 v[100:103], v[144:147], v[168:171], v[100:103]
	v_mfma_f32_16x16x32_bf16 v[92:95], v[152:155], v[168:171], v[92:95]
	v_mfma_f32_16x16x32_bf16 v[84:87], v[144:147], v[176:179], v[84:87]
	v_mfma_f32_16x16x32_bf16 v[80:83], v[152:155], v[176:179], v[80:83]
	v_mfma_f32_16x16x32_bf16 v[68:71], v[144:147], v[184:187], v[68:71]
	v_mfma_f32_16x16x32_bf16 v[64:67], v[152:155], v[184:187], v[64:67]
	v_mfma_f32_16x16x32_bf16 v[116:119], v[148:151], v[164:167], v[116:119]
	v_mfma_f32_16x16x32_bf16 v[108:111], v[156:159], v[164:167], v[108:111]
	v_mfma_f32_16x16x32_bf16 v[100:103], v[148:151], v[172:175], v[100:103]
	v_mfma_f32_16x16x32_bf16 v[92:95], v[156:159], v[172:175], v[92:95]
	v_mfma_f32_16x16x32_bf16 v[84:87], v[148:151], v[180:183], v[84:87]
	v_mfma_f32_16x16x32_bf16 v[80:83], v[156:159], v[180:183], v[80:83]
	v_mfma_f32_16x16x32_bf16 v[68:71], v[148:151], v[188:191], v[68:71]
	v_mfma_f32_16x16x32_bf16 v[64:67], v[156:159], v[188:191], v[64:67]
	s_barrier
	s_add_i32 s51, s44, s33
	v_lshl_add_u64 v[192:193], s[24:25], 0, v[212:213]
	s_mov_b32 m0, s51
	ds_read_b128 v[160:163], v242 offset:16384
	ds_read_b128 v[164:167], v242 offset:17408
	ds_read_b128 v[168:171], v242 offset:18432
	ds_read_b128 v[172:175], v242 offset:19456
	ds_read_b128 v[176:179], v242 offset:20480
	ds_read_b128 v[180:183], v242 offset:21504
	ds_read_b128 v[184:187], v242 offset:22528
	ds_read_b128 v[188:191], v242 offset:23552
	global_load_lds_dwordx4 v[192:193], off
	s_add_i32 m0, s51, 0x2000
	s_add_u32 s52, s24, 0x40000
	v_lshl_add_u64 v[194:195], s[24:25], 0, v[216:217]
	s_addc_u32 s53, s25, 0
	s_add_i32 s51, s45, s33
	global_load_lds_dwordx4 v[194:195], off
	v_lshl_add_u64 v[196:197], s[52:53], 0, v[212:213]
	s_mov_b32 m0, s51
	v_lshl_add_u64 v[198:199], s[26:27], 0, v[214:215]
	global_load_lds_dwordx4 v[196:197], off
	v_lshl_add_u64 v[196:197], s[52:53], 0, v[216:217]
	s_add_i32 m0, s51, 0x2000
	s_nop 0
	global_load_lds_dwordx4 v[196:197], off
	v_lshl_add_u64 v[196:197], s[26:27], 0, v[210:211]
	s_mov_b32 m0, s34
	s_nop 0
	global_load_lds_dwordx4 v[196:197], off
	s_mov_b32 m0, s35
	s_nop 0
	global_load_lds_dwordx4 v[198:199], off
	s_waitcnt vmcnt(8)
	s_waitcnt lgkmcnt(0)
	s_barrier
	s_waitcnt lgkmcnt(0)
	v_mfma_f32_16x16x32_bf16 v[60:63], v[128:131], v[160:163], v[60:63]
	v_mfma_f32_16x16x32_bf16 v[56:59], v[136:139], v[160:163], v[56:59]
	v_mfma_f32_16x16x32_bf16 v[48:51], v[128:131], v[168:171], v[48:51]
	v_mfma_f32_16x16x32_bf16 v[40:43], v[136:139], v[168:171], v[40:43]
	v_mfma_f32_16x16x32_bf16 v[32:35], v[128:131], v[176:179], v[32:35]
	v_mfma_f32_16x16x32_bf16 v[24:27], v[136:139], v[176:179], v[24:27]
	v_mfma_f32_16x16x32_bf16 v[12:15], v[128:131], v[184:187], v[12:15]
	v_mfma_f32_16x16x32_bf16 v[8:11], v[136:139], v[184:187], v[8:11]
	v_mfma_f32_16x16x32_bf16 v[60:63], v[132:135], v[164:167], v[60:63]
	v_mfma_f32_16x16x32_bf16 v[56:59], v[140:143], v[164:167], v[56:59]
	v_mfma_f32_16x16x32_bf16 v[48:51], v[132:135], v[172:175], v[48:51]
	v_mfma_f32_16x16x32_bf16 v[40:43], v[140:143], v[172:175], v[40:43]
	v_mfma_f32_16x16x32_bf16 v[32:35], v[132:135], v[180:183], v[32:35]
	v_mfma_f32_16x16x32_bf16 v[24:27], v[140:143], v[180:183], v[24:27]
	v_mfma_f32_16x16x32_bf16 v[12:15], v[132:135], v[188:191], v[12:15]
	v_mfma_f32_16x16x32_bf16 v[8:11], v[140:143], v[188:191], v[8:11]
	v_mfma_f32_16x16x32_bf16 v[52:55], v[144:147], v[160:163], v[52:55]
	v_mfma_f32_16x16x32_bf16 v[44:47], v[152:155], v[160:163], v[44:47]
	v_mfma_f32_16x16x32_bf16 v[36:39], v[144:147], v[168:171], v[36:39]
	v_mfma_f32_16x16x32_bf16 v[28:31], v[152:155], v[168:171], v[28:31]
	v_mfma_f32_16x16x32_bf16 v[20:23], v[144:147], v[176:179], v[20:23]
	v_mfma_f32_16x16x32_bf16 v[16:19], v[152:155], v[176:179], v[16:19]
	v_mfma_f32_16x16x32_bf16 v[4:7], v[144:147], v[184:187], v[4:7]
	v_mfma_f32_16x16x32_bf16 v[0:3], v[152:155], v[184:187], v[0:3]
	v_mfma_f32_16x16x32_bf16 v[52:55], v[148:151], v[164:167], v[52:55]
	v_mfma_f32_16x16x32_bf16 v[44:47], v[156:159], v[164:167], v[44:47]
	v_mfma_f32_16x16x32_bf16 v[36:39], v[148:151], v[172:175], v[36:39]
	v_mfma_f32_16x16x32_bf16 v[28:31], v[156:159], v[172:175], v[28:31]
	v_mfma_f32_16x16x32_bf16 v[20:23], v[148:151], v[180:183], v[20:23]
	v_mfma_f32_16x16x32_bf16 v[16:19], v[156:159], v[180:183], v[16:19]
	v_mfma_f32_16x16x32_bf16 v[4:7], v[148:151], v[188:191], v[4:7]
	v_mfma_f32_16x16x32_bf16 v[0:3], v[156:159], v[188:191], v[0:3]
	s_barrier
	s_add_i32 s51, 0, 0x18000
	s_add_i32 s52, 0, 0x1c000
	v_add_u32_e32 v140, s51, v238
	v_add_u32_e32 v156, s52, v238
	ds_read_b128 v[128:131], v140
	ds_read_b128 v[132:135], v140 offset:1024
	ds_read_b128 v[136:139], v140 offset:2048
	ds_read_b128 v[140:143], v140 offset:3072
	ds_read_b128 v[144:147], v156
	ds_read_b128 v[148:151], v156 offset:1024
	ds_read_b128 v[152:155], v156 offset:2048
	ds_read_b128 v[156:159], v156 offset:3072
	s_add_u32 s26, s26, 0x40000
	s_addc_u32 s27, s27, 0
	s_mov_b32 m0, s36
	v_lshl_add_u64 v[200:201], s[26:27], 0, v[210:211]
	ds_read_b128 v[160:163], v242 offset:32768
	ds_read_b128 v[164:167], v242 offset:33792
	ds_read_b128 v[168:171], v242 offset:34816
	ds_read_b128 v[172:175], v242 offset:35840
	ds_read_b128 v[176:179], v242 offset:36864
	ds_read_b128 v[180:183], v242 offset:37888
	ds_read_b128 v[184:187], v242 offset:38912
	ds_read_b128 v[188:191], v242 offset:39936
	global_load_lds_dwordx4 v[200:201], off
	v_lshl_add_u64 v[200:201], s[26:27], 0, v[214:215]
	s_mov_b32 m0, s37
	s_nop 0
	global_load_lds_dwordx4 v[200:201], off
	s_waitcnt vmcnt(8)
	s_waitcnt lgkmcnt(0)
	s_barrier
	s_waitcnt lgkmcnt(0)
	v_mfma_f32_16x16x32_bf16 v[124:127], v[128:131], v[160:163], v[124:127]
	v_mfma_f32_16x16x32_bf16 v[120:123], v[136:139], v[160:163], v[120:123]
	v_mfma_f32_16x16x32_bf16 v[112:115], v[128:131], v[168:171], v[112:115]
	v_mfma_f32_16x16x32_bf16 v[104:107], v[136:139], v[168:171], v[104:107]
	v_mfma_f32_16x16x32_bf16 v[96:99], v[128:131], v[176:179], v[96:99]
	v_mfma_f32_16x16x32_bf16 v[88:91], v[136:139], v[176:179], v[88:91]
	v_mfma_f32_16x16x32_bf16 v[76:79], v[128:131], v[184:187], v[76:79]
	v_mfma_f32_16x16x32_bf16 v[72:75], v[136:139], v[184:187], v[72:75]
	v_mfma_f32_16x16x32_bf16 v[124:127], v[132:135], v[164:167], v[124:127]
	v_mfma_f32_16x16x32_bf16 v[120:123], v[140:143], v[164:167], v[120:123]
	v_mfma_f32_16x16x32_bf16 v[112:115], v[132:135], v[172:175], v[112:115]
	v_mfma_f32_16x16x32_bf16 v[104:107], v[140:143], v[172:175], v[104:107]
	v_mfma_f32_16x16x32_bf16 v[96:99], v[132:135], v[180:183], v[96:99]
	v_mfma_f32_16x16x32_bf16 v[88:91], v[140:143], v[180:183], v[88:91]
	v_mfma_f32_16x16x32_bf16 v[76:79], v[132:135], v[188:191], v[76:79]
	v_mfma_f32_16x16x32_bf16 v[72:75], v[140:143], v[188:191], v[72:75]
	v_mfma_f32_16x16x32_bf16 v[116:119], v[144:147], v[160:163], v[116:119]
	v_mfma_f32_16x16x32_bf16 v[108:111], v[152:155], v[160:163], v[108:111]
	v_mfma_f32_16x16x32_bf16 v[100:103], v[144:147], v[168:171], v[100:103]
	v_mfma_f32_16x16x32_bf16 v[92:95], v[152:155], v[168:171], v[92:95]
	v_mfma_f32_16x16x32_bf16 v[84:87], v[144:147], v[176:179], v[84:87]
	v_mfma_f32_16x16x32_bf16 v[80:83], v[152:155], v[176:179], v[80:83]
	v_mfma_f32_16x16x32_bf16 v[68:71], v[144:147], v[184:187], v[68:71]
	v_mfma_f32_16x16x32_bf16 v[64:67], v[152:155], v[184:187], v[64:67]
	v_mfma_f32_16x16x32_bf16 v[116:119], v[148:151], v[164:167], v[116:119]
	v_mfma_f32_16x16x32_bf16 v[108:111], v[156:159], v[164:167], v[108:111]
	v_mfma_f32_16x16x32_bf16 v[100:103], v[148:151], v[172:175], v[100:103]
	v_mfma_f32_16x16x32_bf16 v[92:95], v[156:159], v[172:175], v[92:95]
	v_mfma_f32_16x16x32_bf16 v[84:87], v[148:151], v[180:183], v[84:87]
	v_mfma_f32_16x16x32_bf16 v[80:83], v[156:159], v[180:183], v[80:83]
	v_mfma_f32_16x16x32_bf16 v[68:71], v[148:151], v[188:191], v[68:71]
	v_mfma_f32_16x16x32_bf16 v[64:67], v[156:159], v[188:191], v[64:67]
	s_barrier
	s_add_i32 s26, s51, s33
	v_lshl_add_u64 v[192:193], v[192:193], 0, s[12:13]
	s_mov_b32 m0, s26
	ds_read_b128 v[160:163], v242 offset:49152
	ds_read_b128 v[164:167], v242 offset:50176
	ds_read_b128 v[168:171], v242 offset:51200
	ds_read_b128 v[172:175], v242 offset:52224
	ds_read_b128 v[176:179], v242 offset:53248
	ds_read_b128 v[180:183], v242 offset:54272
	ds_read_b128 v[184:187], v242 offset:55296
	ds_read_b128 v[188:191], v242 offset:56320
	global_load_lds_dwordx4 v[192:193], off
	s_add_i32 m0, s26, 0x2000
	s_add_u32 s24, s24, 0x40080
	v_lshl_add_u64 v[192:193], v[194:195], 0, s[12:13]
	s_addc_u32 s25, s25, 0
	s_add_i32 s26, s52, s33
	global_load_lds_dwordx4 v[192:193], off
	v_lshl_add_u64 v[192:193], s[24:25], 0, v[212:213]
	s_mov_b32 m0, s26
	s_nop 0
	global_load_lds_dwordx4 v[192:193], off
	v_lshl_add_u64 v[192:193], s[24:25], 0, v[216:217]
	s_add_i32 m0, s26, 0x2000
	s_nop 0
	global_load_lds_dwordx4 v[192:193], off
	v_lshl_add_u64 v[192:193], v[196:197], 0, s[12:13]
	s_mov_b32 m0, s39
	s_nop 0
	global_load_lds_dwordx4 v[192:193], off
	v_lshl_add_u64 v[192:193], v[198:199], 0, s[12:13]
	s_mov_b32 m0, s40
	s_nop 0
	global_load_lds_dwordx4 v[192:193], off
	s_waitcnt vmcnt(8)
	s_waitcnt lgkmcnt(0)
	s_barrier
	s_waitcnt lgkmcnt(0)
	v_mfma_f32_16x16x32_bf16 v[60:63], v[128:131], v[160:163], v[60:63]
	v_mfma_f32_16x16x32_bf16 v[56:59], v[136:139], v[160:163], v[56:59]
	v_mfma_f32_16x16x32_bf16 v[48:51], v[128:131], v[168:171], v[48:51]
	v_mfma_f32_16x16x32_bf16 v[40:43], v[136:139], v[168:171], v[40:43]
	v_mfma_f32_16x16x32_bf16 v[32:35], v[128:131], v[176:179], v[32:35]
	v_mfma_f32_16x16x32_bf16 v[24:27], v[136:139], v[176:179], v[24:27]
	v_mfma_f32_16x16x32_bf16 v[12:15], v[128:131], v[184:187], v[12:15]
	v_mfma_f32_16x16x32_bf16 v[8:11], v[136:139], v[184:187], v[8:11]
	v_mfma_f32_16x16x32_bf16 v[60:63], v[132:135], v[164:167], v[60:63]
	v_mfma_f32_16x16x32_bf16 v[56:59], v[140:143], v[164:167], v[56:59]
	v_mfma_f32_16x16x32_bf16 v[48:51], v[132:135], v[172:175], v[48:51]
	v_mfma_f32_16x16x32_bf16 v[40:43], v[140:143], v[172:175], v[40:43]
	v_mfma_f32_16x16x32_bf16 v[32:35], v[132:135], v[180:183], v[32:35]
	v_mfma_f32_16x16x32_bf16 v[24:27], v[140:143], v[180:183], v[24:27]
	v_mfma_f32_16x16x32_bf16 v[12:15], v[132:135], v[188:191], v[12:15]
	v_mfma_f32_16x16x32_bf16 v[8:11], v[140:143], v[188:191], v[8:11]
	v_mfma_f32_16x16x32_bf16 v[52:55], v[144:147], v[160:163], v[52:55]
	v_mfma_f32_16x16x32_bf16 v[44:47], v[152:155], v[160:163], v[44:47]
	v_mfma_f32_16x16x32_bf16 v[36:39], v[144:147], v[168:171], v[36:39]
	v_mfma_f32_16x16x32_bf16 v[28:31], v[152:155], v[168:171], v[28:31]
	v_mfma_f32_16x16x32_bf16 v[20:23], v[144:147], v[176:179], v[20:23]
	v_mfma_f32_16x16x32_bf16 v[16:19], v[152:155], v[176:179], v[16:19]
	v_mfma_f32_16x16x32_bf16 v[4:7], v[144:147], v[184:187], v[4:7]
	v_mfma_f32_16x16x32_bf16 v[0:3], v[152:155], v[184:187], v[0:3]
	v_mfma_f32_16x16x32_bf16 v[52:55], v[148:151], v[164:167], v[52:55]
	v_mfma_f32_16x16x32_bf16 v[44:47], v[156:159], v[164:167], v[44:47]
	v_mfma_f32_16x16x32_bf16 v[36:39], v[148:151], v[172:175], v[36:39]
	v_mfma_f32_16x16x32_bf16 v[28:31], v[156:159], v[172:175], v[28:31]
	v_mfma_f32_16x16x32_bf16 v[20:23], v[148:151], v[180:183], v[20:23]
	v_mfma_f32_16x16x32_bf16 v[16:19], v[156:159], v[180:183], v[16:19]
	v_mfma_f32_16x16x32_bf16 v[4:7], v[148:151], v[188:191], v[4:7]
	v_mfma_f32_16x16x32_bf16 v[0:3], v[156:159], v[188:191], v[0:3]
	s_barrier
	s_add_i32 s50, s50, 2
	s_add_u32 s22, s22, 0x100
	s_addc_u32 s23, s23, 0
	s_add_u32 s48, s48, 0x100
	s_addc_u32 s49, s49, 0
	s_cmp_gt_u32 s50, 13
	s_cbranch_scc0 .LBB0_1028
	s_cmp_gt_i32 s4, 63
	v_lshl_or_b32 v128, s5, 8, v239
	s_cselect_b64 s[22:23], -1, 0
	s_lshl_b32 s5, s4, 2
	s_add_i32 s17, s41, s5
	s_ashr_i32 s15, s4, 3
	s_cmp_lt_i32 s4, 64
	v_lshl_add_u32 v228, s4, 8, v237
	s_cselect_b64 s[4:5], -1, 0
	v_add_u32_e32 v130, 0xffffc000, v228
	s_and_b64 vcc, s[4:5], exec
	v_cndmask_b32_e64 v144, v130, v228, s[4:5]
	s_cselect_b32 s24, s15, s17
	s_mul_i32 s26, s24, 0x9000
	v_ashrrev_i32_e32 v145, 31, v144
	v_ashrrev_i32_e32 v129, 31, v128
	s_mul_hi_i32 s27, s24, 0x9000
	s_cselect_b32 s25, s73, s7
	s_cselect_b32 s24, s72, s6
	s_add_u32 s26, s10, s26
	v_lshlrev_b64 v[144:145], 12, v[144:145]
	s_addc_u32 s27, s11, s27
	v_lshlrev_b64 v[226:227], 2, v[128:129]
	v_lshl_add_u64 v[144:145], s[24:25], 0, v[144:145]
	v_lshl_add_u64 v[136:137], s[26:27], 0, v[226:227]
	v_lshl_add_u64 v[144:145], v[144:145], 0, v[226:227]
	global_load_dwordx4 v[132:135], v[136:137], off offset:16
	global_load_dwordx4 v[140:143], v[136:137], off
	global_load_dwordx4 v[128:131], v[136:137], off offset:528
	s_nop 0
	global_load_dwordx4 v[136:139], v[136:137], off offset:512
	s_nop 0
	global_load_dwordx4 v[200:203], v[144:145], off offset:16
	global_load_dwordx4 v[204:207], v[144:145], off
	global_load_dwordx4 v[192:195], v[144:145], off offset:528
	global_load_dwordx4 v[196:199], v[144:145], off offset:512
	v_or_b32_e32 v230, 16, v228
	v_add_u32_e32 v144, 0xffffc010, v228
	v_cndmask_b32_e64 v144, v144, v230, s[4:5]
	v_ashrrev_i32_e32 v145, 31, v144
	v_lshlrev_b64 v[144:145], 12, v[144:145]
	v_lshl_add_u64 v[144:145], s[24:25], 0, v[144:145]
	v_lshl_add_u64 v[144:145], v[144:145], 0, v[226:227]
	global_load_dwordx4 v[184:187], v[144:145], off offset:16
	global_load_dwordx4 v[188:191], v[144:145], off
	global_load_dwordx4 v[176:179], v[144:145], off offset:528
	global_load_dwordx4 v[180:183], v[144:145], off offset:512
	v_or_b32_e32 v232, 32, v228
	v_add_u32_e32 v144, 0xffffc020, v228
	v_cndmask_b32_e64 v144, v144, v232, s[4:5]
	v_ashrrev_i32_e32 v145, 31, v144
	v_lshlrev_b64 v[144:145], 12, v[144:145]
	v_lshl_add_u64 v[144:145], s[24:25], 0, v[144:145]
	v_lshl_add_u64 v[144:145], v[144:145], 0, v[226:227]
	global_load_dwordx4 v[168:171], v[144:145], off offset:16
	global_load_dwordx4 v[172:175], v[144:145], off
	global_load_dwordx4 v[160:163], v[144:145], off offset:528
	global_load_dwordx4 v[164:167], v[144:145], off offset:512
	v_or_b32_e32 v146, 48, v228
	s_mov_b64 s[26:27], -1
	v_ashrrev_i32_e32 v147, 31, v146
	s_cbranch_vccnz .LBB0_1031
	v_add_u32_e32 v144, 0xffffc030, v228
	v_ashrrev_i32_e32 v145, 31, v144
	v_lshlrev_b64 v[144:145], 12, v[144:145]
	v_lshl_add_u64 v[144:145], s[6:7], 0, v[144:145]
	v_lshlrev_b64 v[234:235], 12, v[146:147]
	s_mov_b64 s[26:27], 0

.LBB0_1219:
	ds_read_b128 v[150:153], v147
	ds_read_b128 v[154:157], v147 offset:1024
	ds_read_b128 v[158:161], v147 offset:2048
	ds_read_b128 v[162:165], v147 offset:3072
	ds_read_b128 v[166:169], v148
	ds_read_b128 v[170:173], v148 offset:1024
	ds_read_b128 v[174:177], v148 offset:2048
	ds_read_b128 v[178:181], v148 offset:3072
	s_add_u32 s24, s22, 0xfffc0080
	s_addc_u32 s25, s23, -1
	s_cmp_eq_u32 s48, 12
	s_cselect_b32 s27, s15, s25
	s_cselect_b32 s26, s44, s24
	s_cselect_b32 s25, s13, s47
	s_cselect_b32 s24, s45, s46
	v_lshl_add_u64 v[206:207], s[22:23], 0, v[136:137]
	s_add_i32 m0, s21, 0xc000
	ds_read_b128 v[182:185], v149
	ds_read_b128 v[186:189], v149 offset:1024
	ds_read_b128 v[190:193], v149 offset:2048
	ds_read_b128 v[194:197], v149 offset:3072
	ds_read_b128 v[198:201], v149 offset:4096
	ds_read_b128 v[202:205], v149 offset:5120
	ds_read_b128 v[210:213], v149 offset:6144
	ds_read_b128 v[214:217], v149 offset:7168
	global_load_lds_dwordx4 v[206:207], off
	v_lshl_add_u64 v[206:207], s[22:23], 0, v[138:139]
	s_add_i32 m0, s21, 0xe000
	s_nop 0
	global_load_lds_dwordx4 v[206:207], off
	s_waitcnt vmcnt(8)
	s_waitcnt lgkmcnt(0)
	s_barrier
	s_waitcnt lgkmcnt(0)
	v_mfma_f32_16x16x32_bf16 v[124:127], v[150:153], v[182:185], v[124:127]
	v_mfma_f32_16x16x32_bf16 v[120:123], v[158:161], v[182:185], v[120:123]
	v_mfma_f32_16x16x32_bf16 v[108:111], v[150:153], v[190:193], v[108:111]
	v_mfma_f32_16x16x32_bf16 v[104:107], v[158:161], v[190:193], v[104:107]
	v_mfma_f32_16x16x32_bf16 v[92:95], v[150:153], v[198:201], v[92:95]
	v_mfma_f32_16x16x32_bf16 v[88:91], v[158:161], v[198:201], v[88:91]
	v_mfma_f32_16x16x32_bf16 v[76:79], v[150:153], v[210:213], v[76:79]
	v_mfma_f32_16x16x32_bf16 v[72:75], v[158:161], v[210:213], v[72:75]
	v_mfma_f32_16x16x32_bf16 v[124:127], v[154:157], v[186:189], v[124:127]
	v_mfma_f32_16x16x32_bf16 v[120:123], v[162:165], v[186:189], v[120:123]
	v_mfma_f32_16x16x32_bf16 v[108:111], v[154:157], v[194:197], v[108:111]
	v_mfma_f32_16x16x32_bf16 v[104:107], v[162:165], v[194:197], v[104:107]
	v_mfma_f32_16x16x32_bf16 v[92:95], v[154:157], v[202:205], v[92:95]
	v_mfma_f32_16x16x32_bf16 v[88:91], v[162:165], v[202:205], v[88:91]
	v_mfma_f32_16x16x32_bf16 v[76:79], v[154:157], v[214:217], v[76:79]
	v_mfma_f32_16x16x32_bf16 v[72:75], v[162:165], v[214:217], v[72:75]
	v_mfma_f32_16x16x32_bf16 v[116:119], v[166:169], v[182:185], v[116:119]
	v_mfma_f32_16x16x32_bf16 v[112:115], v[174:177], v[182:185], v[112:115]
	v_mfma_f32_16x16x32_bf16 v[100:103], v[166:169], v[190:193], v[100:103]
	v_mfma_f32_16x16x32_bf16 v[96:99], v[174:177], v[190:193], v[96:99]
	v_mfma_f32_16x16x32_bf16 v[84:87], v[166:169], v[198:201], v[84:87]
	v_mfma_f32_16x16x32_bf16 v[80:83], v[174:177], v[198:201], v[80:83]
	v_mfma_f32_16x16x32_bf16 v[68:71], v[166:169], v[210:213], v[68:71]
	v_mfma_f32_16x16x32_bf16 v[64:67], v[174:177], v[210:213], v[64:67]
	v_mfma_f32_16x16x32_bf16 v[116:119], v[170:173], v[186:189], v[116:119]
	v_mfma_f32_16x16x32_bf16 v[112:115], v[178:181], v[186:189], v[112:115]
	v_mfma_f32_16x16x32_bf16 v[100:103], v[170:173], v[194:197], v[100:103]
	v_mfma_f32_16x16x32_bf16 v[96:99], v[178:181], v[194:197], v[96:99]
	v_mfma_f32_16x16x32_bf16 v[84:87], v[170:173], v[202:205], v[84:87]
	v_mfma_f32_16x16x32_bf16 v[80:83], v[178:181], v[202:205], v[80:83]
	v_mfma_f32_16x16x32_bf16 v[68:71], v[170:173], v[214:217], v[68:71]
	v_mfma_f32_16x16x32_bf16 v[64:67], v[178:181], v[214:217], v[64:67]
	s_barrier
	s_add_i32 s49, s40, s28
	v_lshl_add_u64 v[206:207], s[24:25], 0, v[132:133]
	s_mov_b32 m0, s49
	ds_read_b128 v[182:185], v149 offset:16384
	ds_read_b128 v[186:189], v149 offset:17408
	ds_read_b128 v[190:193], v149 offset:18432
	ds_read_b128 v[194:197], v149 offset:19456
	ds_read_b128 v[198:201], v149 offset:20480
	ds_read_b128 v[202:205], v149 offset:21504
	ds_read_b128 v[210:213], v149 offset:22528
	ds_read_b128 v[214:217], v149 offset:23552
	global_load_lds_dwordx4 v[206:207], off
	s_add_i32 m0, s49, 0x2000
	s_add_u32 s50, s24, 0x40000
	v_lshl_add_u64 v[218:219], s[24:25], 0, v[128:129]
	s_addc_u32 s51, s25, 0
	s_add_i32 s49, s41, s28
	global_load_lds_dwordx4 v[218:219], off
	v_lshl_add_u64 v[220:221], s[50:51], 0, v[132:133]
	s_mov_b32 m0, s49
	v_lshl_add_u64 v[222:223], s[26:27], 0, v[130:131]
	global_load_lds_dwordx4 v[220:221], off
	v_lshl_add_u64 v[220:221], s[50:51], 0, v[128:129]
	s_add_i32 m0, s49, 0x2000
	s_nop 0
	global_load_lds_dwordx4 v[220:221], off
	v_lshl_add_u64 v[220:221], s[26:27], 0, v[134:135]
	s_mov_b32 m0, s21
	s_nop 0
	global_load_lds_dwordx4 v[220:221], off
	s_mov_b32 m0, s31
	s_nop 0
	global_load_lds_dwordx4 v[222:223], off
	s_waitcnt vmcnt(8)
	s_waitcnt lgkmcnt(0)
	s_barrier
	s_waitcnt lgkmcnt(0)
	v_mfma_f32_16x16x32_bf16 v[60:63], v[150:153], v[182:185], v[60:63]
	v_mfma_f32_16x16x32_bf16 v[56:59], v[158:161], v[182:185], v[56:59]
	v_mfma_f32_16x16x32_bf16 v[44:47], v[150:153], v[190:193], v[44:47]
	v_mfma_f32_16x16x32_bf16 v[40:43], v[158:161], v[190:193], v[40:43]
	v_mfma_f32_16x16x32_bf16 v[28:31], v[150:153], v[198:201], v[28:31]
	v_mfma_f32_16x16x32_bf16 v[24:27], v[158:161], v[198:201], v[24:27]
	v_mfma_f32_16x16x32_bf16 v[12:15], v[150:153], v[210:213], v[12:15]
	v_mfma_f32_16x16x32_bf16 v[8:11], v[158:161], v[210:213], v[8:11]
	v_mfma_f32_16x16x32_bf16 v[60:63], v[154:157], v[186:189], v[60:63]
	v_mfma_f32_16x16x32_bf16 v[56:59], v[162:165], v[186:189], v[56:59]
	v_mfma_f32_16x16x32_bf16 v[44:47], v[154:157], v[194:197], v[44:47]
	v_mfma_f32_16x16x32_bf16 v[40:43], v[162:165], v[194:197], v[40:43]
	v_mfma_f32_16x16x32_bf16 v[28:31], v[154:157], v[202:205], v[28:31]
	v_mfma_f32_16x16x32_bf16 v[24:27], v[162:165], v[202:205], v[24:27]
	v_mfma_f32_16x16x32_bf16 v[12:15], v[154:157], v[214:217], v[12:15]
	v_mfma_f32_16x16x32_bf16 v[8:11], v[162:165], v[214:217], v[8:11]
	v_mfma_f32_16x16x32_bf16 v[52:55], v[166:169], v[182:185], v[52:55]
	v_mfma_f32_16x16x32_bf16 v[48:51], v[174:177], v[182:185], v[48:51]
	v_mfma_f32_16x16x32_bf16 v[36:39], v[166:169], v[190:193], v[36:39]
	v_mfma_f32_16x16x32_bf16 v[32:35], v[174:177], v[190:193], v[32:35]
	v_mfma_f32_16x16x32_bf16 v[20:23], v[166:169], v[198:201], v[20:23]
	v_mfma_f32_16x16x32_bf16 v[16:19], v[174:177], v[198:201], v[16:19]
	v_mfma_f32_16x16x32_bf16 v[4:7], v[166:169], v[210:213], v[4:7]
	v_mfma_f32_16x16x32_bf16 v[0:3], v[174:177], v[210:213], v[0:3]
	v_mfma_f32_16x16x32_bf16 v[52:55], v[170:173], v[186:189], v[52:55]
	v_mfma_f32_16x16x32_bf16 v[48:51], v[178:181], v[186:189], v[48:51]
	v_mfma_f32_16x16x32_bf16 v[36:39], v[170:173], v[194:197], v[36:39]
	v_mfma_f32_16x16x32_bf16 v[32:35], v[178:181], v[194:197], v[32:35]
	v_mfma_f32_16x16x32_bf16 v[20:23], v[170:173], v[202:205], v[20:23]
	v_mfma_f32_16x16x32_bf16 v[16:19], v[178:181], v[202:205], v[16:19]
	v_mfma_f32_16x16x32_bf16 v[4:7], v[170:173], v[214:217], v[4:7]
	v_mfma_f32_16x16x32_bf16 v[0:3], v[178:181], v[214:217], v[0:3]
	s_barrier
	s_add_i32 s49, 0, 0x18000
	s_add_i32 s50, 0, 0x1c000
	v_add_u32_e32 v162, s49, v145
	v_add_u32_e32 v178, s50, v145
	ds_read_b128 v[150:153], v162
	ds_read_b128 v[154:157], v162 offset:1024
	ds_read_b128 v[158:161], v162 offset:2048
	ds_read_b128 v[162:165], v162 offset:3072
	ds_read_b128 v[166:169], v178
	ds_read_b128 v[170:173], v178 offset:1024
	ds_read_b128 v[174:177], v178 offset:2048
	ds_read_b128 v[178:181], v178 offset:3072
	s_add_u32 s26, s26, 0x40000
	s_addc_u32 s27, s27, 0
	s_mov_b32 m0, s33
	v_lshl_add_u64 v[224:225], s[26:27], 0, v[134:135]
	ds_read_b128 v[182:185], v149 offset:32768
	ds_read_b128 v[186:189], v149 offset:33792
	ds_read_b128 v[190:193], v149 offset:34816
	ds_read_b128 v[194:197], v149 offset:35840
	ds_read_b128 v[198:201], v149 offset:36864
	ds_read_b128 v[202:205], v149 offset:37888
	ds_read_b128 v[210:213], v149 offset:38912
	ds_read_b128 v[214:217], v149 offset:39936
	global_load_lds_dwordx4 v[224:225], off
	v_lshl_add_u64 v[224:225], s[26:27], 0, v[130:131]
	s_mov_b32 m0, s34
	s_nop 0
	global_load_lds_dwordx4 v[224:225], off
	s_waitcnt vmcnt(8)
	s_waitcnt lgkmcnt(0)
	s_barrier
	s_waitcnt lgkmcnt(0)
	v_mfma_f32_16x16x32_bf16 v[124:127], v[150:153], v[182:185], v[124:127]
	v_mfma_f32_16x16x32_bf16 v[120:123], v[158:161], v[182:185], v[120:123]
	v_mfma_f32_16x16x32_bf16 v[108:111], v[150:153], v[190:193], v[108:111]
	v_mfma_f32_16x16x32_bf16 v[104:107], v[158:161], v[190:193], v[104:107]
	v_mfma_f32_16x16x32_bf16 v[92:95], v[150:153], v[198:201], v[92:95]
	v_mfma_f32_16x16x32_bf16 v[88:91], v[158:161], v[198:201], v[88:91]
	v_mfma_f32_16x16x32_bf16 v[76:79], v[150:153], v[210:213], v[76:79]
	v_mfma_f32_16x16x32_bf16 v[72:75], v[158:161], v[210:213], v[72:75]
	v_mfma_f32_16x16x32_bf16 v[124:127], v[154:157], v[186:189], v[124:127]
	v_mfma_f32_16x16x32_bf16 v[120:123], v[162:165], v[186:189], v[120:123]
	v_mfma_f32_16x16x32_bf16 v[108:111], v[154:157], v[194:197], v[108:111]
	v_mfma_f32_16x16x32_bf16 v[104:107], v[162:165], v[194:197], v[104:107]
	v_mfma_f32_16x16x32_bf16 v[92:95], v[154:157], v[202:205], v[92:95]
	v_mfma_f32_16x16x32_bf16 v[88:91], v[162:165], v[202:205], v[88:91]
	v_mfma_f32_16x16x32_bf16 v[76:79], v[154:157], v[214:217], v[76:79]
	v_mfma_f32_16x16x32_bf16 v[72:75], v[162:165], v[214:217], v[72:75]
	v_mfma_f32_16x16x32_bf16 v[116:119], v[166:169], v[182:185], v[116:119]
	v_mfma_f32_16x16x32_bf16 v[112:115], v[174:177], v[182:185], v[112:115]
	v_mfma_f32_16x16x32_bf16 v[100:103], v[166:169], v[190:193], v[100:103]
	v_mfma_f32_16x16x32_bf16 v[96:99], v[174:177], v[190:193], v[96:99]
	v_mfma_f32_16x16x32_bf16 v[84:87], v[166:169], v[198:201], v[84:87]
	v_mfma_f32_16x16x32_bf16 v[80:83], v[174:177], v[198:201], v[80:83]
	v_mfma_f32_16x16x32_bf16 v[68:71], v[166:169], v[210:213], v[68:71]
	v_mfma_f32_16x16x32_bf16 v[64:67], v[174:177], v[210:213], v[64:67]
	v_mfma_f32_16x16x32_bf16 v[116:119], v[170:173], v[186:189], v[116:119]
	v_mfma_f32_16x16x32_bf16 v[112:115], v[178:181], v[186:189], v[112:115]
	v_mfma_f32_16x16x32_bf16 v[100:103], v[170:173], v[194:197], v[100:103]
	v_mfma_f32_16x16x32_bf16 v[96:99], v[178:181], v[194:197], v[96:99]
	v_mfma_f32_16x16x32_bf16 v[84:87], v[170:173], v[202:205], v[84:87]
	v_mfma_f32_16x16x32_bf16 v[80:83], v[178:181], v[202:205], v[80:83]
	v_mfma_f32_16x16x32_bf16 v[68:71], v[170:173], v[214:217], v[68:71]
	v_mfma_f32_16x16x32_bf16 v[64:67], v[178:181], v[214:217], v[64:67]
	s_barrier
	s_add_i32 s26, s49, s28
	v_lshl_add_u64 v[206:207], v[206:207], 0, s[8:9]
	s_mov_b32 m0, s26
	ds_read_b128 v[182:185], v149 offset:49152
	ds_read_b128 v[186:189], v149 offset:50176
	ds_read_b128 v[190:193], v149 offset:51200
	ds_read_b128 v[194:197], v149 offset:52224
	ds_read_b128 v[198:201], v149 offset:53248
	ds_read_b128 v[202:205], v149 offset:54272
	ds_read_b128 v[210:213], v149 offset:55296
	ds_read_b128 v[214:217], v149 offset:56320
	global_load_lds_dwordx4 v[206:207], off
	s_add_i32 m0, s26, 0x2000
	s_add_u32 s24, s24, 0x40080
	v_lshl_add_u64 v[206:207], v[218:219], 0, s[8:9]
	s_addc_u32 s25, s25, 0
	s_add_i32 s26, s50, s28
	global_load_lds_dwordx4 v[206:207], off
	v_lshl_add_u64 v[206:207], s[24:25], 0, v[132:133]
	s_mov_b32 m0, s26
	s_nop 0
	global_load_lds_dwordx4 v[206:207], off
	v_lshl_add_u64 v[206:207], s[24:25], 0, v[128:129]
	s_add_i32 m0, s26, 0x2000
	s_nop 0
	global_load_lds_dwordx4 v[206:207], off
	v_lshl_add_u64 v[206:207], v[220:221], 0, s[8:9]
	s_mov_b32 m0, s36
	s_nop 0
	global_load_lds_dwordx4 v[206:207], off
	v_lshl_add_u64 v[206:207], v[222:223], 0, s[8:9]
	s_mov_b32 m0, s37
	s_nop 0
	global_load_lds_dwordx4 v[206:207], off
	s_waitcnt vmcnt(8)
	s_waitcnt lgkmcnt(0)
	s_barrier
	s_waitcnt lgkmcnt(0)
	v_mfma_f32_16x16x32_bf16 v[60:63], v[150:153], v[182:185], v[60:63]
	v_mfma_f32_16x16x32_bf16 v[56:59], v[158:161], v[182:185], v[56:59]
	v_mfma_f32_16x16x32_bf16 v[44:47], v[150:153], v[190:193], v[44:47]
	v_mfma_f32_16x16x32_bf16 v[40:43], v[158:161], v[190:193], v[40:43]
	v_mfma_f32_16x16x32_bf16 v[28:31], v[150:153], v[198:201], v[28:31]
	v_mfma_f32_16x16x32_bf16 v[24:27], v[158:161], v[198:201], v[24:27]
	v_mfma_f32_16x16x32_bf16 v[12:15], v[150:153], v[210:213], v[12:15]
	v_mfma_f32_16x16x32_bf16 v[8:11], v[158:161], v[210:213], v[8:11]
	v_mfma_f32_16x16x32_bf16 v[60:63], v[154:157], v[186:189], v[60:63]
	v_mfma_f32_16x16x32_bf16 v[56:59], v[162:165], v[186:189], v[56:59]
	v_mfma_f32_16x16x32_bf16 v[44:47], v[154:157], v[194:197], v[44:47]
	v_mfma_f32_16x16x32_bf16 v[40:43], v[162:165], v[194:197], v[40:43]
	v_mfma_f32_16x16x32_bf16 v[28:31], v[154:157], v[202:205], v[28:31]
	v_mfma_f32_16x16x32_bf16 v[24:27], v[162:165], v[202:205], v[24:27]
	v_mfma_f32_16x16x32_bf16 v[12:15], v[154:157], v[214:217], v[12:15]
	v_mfma_f32_16x16x32_bf16 v[8:11], v[162:165], v[214:217], v[8:11]
	v_mfma_f32_16x16x32_bf16 v[52:55], v[166:169], v[182:185], v[52:55]
	v_mfma_f32_16x16x32_bf16 v[48:51], v[174:177], v[182:185], v[48:51]
	v_mfma_f32_16x16x32_bf16 v[36:39], v[166:169], v[190:193], v[36:39]
	v_mfma_f32_16x16x32_bf16 v[32:35], v[174:177], v[190:193], v[32:35]
	v_mfma_f32_16x16x32_bf16 v[20:23], v[166:169], v[198:201], v[20:23]
	v_mfma_f32_16x16x32_bf16 v[16:19], v[174:177], v[198:201], v[16:19]
	v_mfma_f32_16x16x32_bf16 v[4:7], v[166:169], v[210:213], v[4:7]
	v_mfma_f32_16x16x32_bf16 v[0:3], v[174:177], v[210:213], v[0:3]
	v_mfma_f32_16x16x32_bf16 v[52:55], v[170:173], v[186:189], v[52:55]
	v_mfma_f32_16x16x32_bf16 v[48:51], v[178:181], v[186:189], v[48:51]
	v_mfma_f32_16x16x32_bf16 v[36:39], v[170:173], v[194:197], v[36:39]
	v_mfma_f32_16x16x32_bf16 v[32:35], v[178:181], v[194:197], v[32:35]
	v_mfma_f32_16x16x32_bf16 v[20:23], v[170:173], v[202:205], v[20:23]
	v_mfma_f32_16x16x32_bf16 v[16:19], v[178:181], v[202:205], v[16:19]
	v_mfma_f32_16x16x32_bf16 v[4:7], v[170:173], v[214:217], v[4:7]
	v_mfma_f32_16x16x32_bf16 v[0:3], v[178:181], v[214:217], v[0:3]
	s_barrier
	s_add_i32 s48, s48, 2
	s_add_u32 s22, s22, 0x100
	s_addc_u32 s23, s23, 0
	s_add_u32 s46, s46, 0x100
	s_addc_u32 s47, s47, 0
	s_cmp_gt_u32 s48, 13
	s_cbranch_scc0 .LBB0_1219
	s_and_b64 vcc, exec, s[10:11]
	s_cbranch_vccz .LBB0_1222
	s_barrier

.LBB0_1318:
	ds_read_b128 v[128:131], v240
	ds_read_b128 v[132:135], v240 offset:1024
	ds_read_b128 v[136:139], v240 offset:2048
	ds_read_b128 v[140:143], v240 offset:3072
	ds_read_b128 v[144:147], v241
	ds_read_b128 v[148:151], v241 offset:1024
	ds_read_b128 v[152:155], v241 offset:2048
	ds_read_b128 v[156:159], v241 offset:3072
	s_add_u32 s20, s4, 0xfff50080
	s_addc_u32 s21, s5, -1
	s_cmp_eq_u32 s46, 40
	s_cselect_b32 s23, s19, s21
	s_cselect_b32 s22, s18, s20
	s_cselect_b32 s21, s7, s45
	s_cselect_b32 s20, s6, s44
	v_lshl_add_u64 v[192:193], s[4:5], 0, v[218:219]
	s_add_i32 m0, s29, 0xc000
	ds_read_b128 v[160:163], v242
	ds_read_b128 v[164:167], v242 offset:1024
	ds_read_b128 v[168:171], v242 offset:2048
	ds_read_b128 v[172:175], v242 offset:3072
	ds_read_b128 v[176:179], v242 offset:4096
	ds_read_b128 v[180:183], v242 offset:5120
	ds_read_b128 v[184:187], v242 offset:6144
	ds_read_b128 v[188:191], v242 offset:7168
	global_load_lds_dwordx4 v[192:193], off
	v_lshl_add_u64 v[192:193], s[4:5], 0, v[220:221]
	s_add_i32 m0, s29, 0xe000
	s_nop 0
	global_load_lds_dwordx4 v[192:193], off
	s_waitcnt vmcnt(8)
	s_waitcnt lgkmcnt(0)
	s_barrier
	s_waitcnt lgkmcnt(0)
	v_mfma_f32_16x16x32_bf16 v[124:127], v[128:131], v[160:163], v[124:127]
	v_mfma_f32_16x16x32_bf16 v[120:123], v[136:139], v[160:163], v[120:123]
	v_mfma_f32_16x16x32_bf16 v[116:119], v[128:131], v[168:171], v[116:119]
	v_mfma_f32_16x16x32_bf16 v[112:115], v[136:139], v[168:171], v[112:115]
	v_mfma_f32_16x16x32_bf16 v[108:111], v[128:131], v[176:179], v[108:111]
	v_mfma_f32_16x16x32_bf16 v[100:103], v[136:139], v[176:179], v[100:103]
	v_mfma_f32_16x16x32_bf16 v[80:83], v[128:131], v[184:187], v[80:83]
	v_mfma_f32_16x16x32_bf16 v[72:75], v[136:139], v[184:187], v[72:75]
	v_mfma_f32_16x16x32_bf16 v[124:127], v[132:135], v[164:167], v[124:127]
	v_mfma_f32_16x16x32_bf16 v[120:123], v[140:143], v[164:167], v[120:123]
	v_mfma_f32_16x16x32_bf16 v[116:119], v[132:135], v[172:175], v[116:119]
	v_mfma_f32_16x16x32_bf16 v[112:115], v[140:143], v[172:175], v[112:115]
	v_mfma_f32_16x16x32_bf16 v[108:111], v[132:135], v[180:183], v[108:111]
	v_mfma_f32_16x16x32_bf16 v[100:103], v[140:143], v[180:183], v[100:103]
	v_mfma_f32_16x16x32_bf16 v[80:83], v[132:135], v[188:191], v[80:83]
	v_mfma_f32_16x16x32_bf16 v[72:75], v[140:143], v[188:191], v[72:75]
	v_mfma_f32_16x16x32_bf16 v[104:107], v[144:147], v[160:163], v[104:107]
	v_mfma_f32_16x16x32_bf16 v[96:99], v[152:155], v[160:163], v[96:99]
	v_mfma_f32_16x16x32_bf16 v[92:95], v[144:147], v[168:171], v[92:95]
	v_mfma_f32_16x16x32_bf16 v[88:91], v[152:155], v[168:171], v[88:91]
	v_mfma_f32_16x16x32_bf16 v[84:87], v[144:147], v[176:179], v[84:87]
	v_mfma_f32_16x16x32_bf16 v[76:79], v[152:155], v[176:179], v[76:79]
	v_mfma_f32_16x16x32_bf16 v[68:71], v[144:147], v[184:187], v[68:71]
	v_mfma_f32_16x16x32_bf16 v[64:67], v[152:155], v[184:187], v[64:67]
	v_mfma_f32_16x16x32_bf16 v[104:107], v[148:151], v[164:167], v[104:107]
	v_mfma_f32_16x16x32_bf16 v[96:99], v[156:159], v[164:167], v[96:99]
	v_mfma_f32_16x16x32_bf16 v[92:95], v[148:151], v[172:175], v[92:95]
	v_mfma_f32_16x16x32_bf16 v[88:91], v[156:159], v[172:175], v[88:91]
	v_mfma_f32_16x16x32_bf16 v[84:87], v[148:151], v[180:183], v[84:87]
	v_mfma_f32_16x16x32_bf16 v[76:79], v[156:159], v[180:183], v[76:79]
	v_mfma_f32_16x16x32_bf16 v[68:71], v[148:151], v[188:191], v[68:71]
	v_mfma_f32_16x16x32_bf16 v[64:67], v[156:159], v[188:191], v[64:67]
	s_barrier
	s_add_i32 s47, s40, s28
	v_lshl_add_u64 v[192:193], s[20:21], 0, v[212:213]
	s_mov_b32 m0, s47
	ds_read_b128 v[160:163], v242 offset:16384
	ds_read_b128 v[164:167], v242 offset:17408
	ds_read_b128 v[168:171], v242 offset:18432
	ds_read_b128 v[172:175], v242 offset:19456
	ds_read_b128 v[176:179], v242 offset:20480
	ds_read_b128 v[180:183], v242 offset:21504
	ds_read_b128 v[184:187], v242 offset:22528
	ds_read_b128 v[188:191], v242 offset:23552
	global_load_lds_dwordx4 v[192:193], off
	s_add_i32 m0, s47, 0x2000
	s_add_u32 s48, s20, 0xb0000
	v_lshl_add_u64 v[194:195], s[20:21], 0, v[216:217]
	s_addc_u32 s49, s21, 0
	s_add_i32 s47, s41, s28
	global_load_lds_dwordx4 v[194:195], off
	v_lshl_add_u64 v[196:197], s[48:49], 0, v[212:213]
	s_mov_b32 m0, s47
	v_lshl_add_u64 v[198:199], s[22:23], 0, v[214:215]
	global_load_lds_dwordx4 v[196:197], off
	v_lshl_add_u64 v[196:197], s[48:49], 0, v[216:217]
	s_add_i32 m0, s47, 0x2000
	s_nop 0
	global_load_lds_dwordx4 v[196:197], off
	v_lshl_add_u64 v[196:197], s[22:23], 0, v[210:211]
	s_mov_b32 m0, s29
	s_nop 0
	global_load_lds_dwordx4 v[196:197], off
	s_mov_b32 m0, s30
	s_nop 0
	global_load_lds_dwordx4 v[198:199], off
	s_waitcnt vmcnt(8)
	s_waitcnt lgkmcnt(0)
	s_barrier
	s_waitcnt lgkmcnt(0)
	v_mfma_f32_16x16x32_bf16 v[60:63], v[128:131], v[160:163], v[60:63]
	v_mfma_f32_16x16x32_bf16 v[56:59], v[136:139], v[160:163], v[56:59]
	v_mfma_f32_16x16x32_bf16 v[52:55], v[128:131], v[168:171], v[52:55]
	v_mfma_f32_16x16x32_bf16 v[48:51], v[136:139], v[168:171], v[48:51]
	v_mfma_f32_16x16x32_bf16 v[44:47], v[128:131], v[176:179], v[44:47]
	v_mfma_f32_16x16x32_bf16 v[36:39], v[136:139], v[176:179], v[36:39]
	v_mfma_f32_16x16x32_bf16 v[20:23], v[128:131], v[184:187], v[20:23]
	v_mfma_f32_16x16x32_bf16 v[12:15], v[136:139], v[184:187], v[12:15]
	v_mfma_f32_16x16x32_bf16 v[60:63], v[132:135], v[164:167], v[60:63]
	v_mfma_f32_16x16x32_bf16 v[56:59], v[140:143], v[164:167], v[56:59]
	v_mfma_f32_16x16x32_bf16 v[52:55], v[132:135], v[172:175], v[52:55]
	v_mfma_f32_16x16x32_bf16 v[48:51], v[140:143], v[172:175], v[48:51]
	v_mfma_f32_16x16x32_bf16 v[44:47], v[132:135], v[180:183], v[44:47]
	v_mfma_f32_16x16x32_bf16 v[36:39], v[140:143], v[180:183], v[36:39]
	v_mfma_f32_16x16x32_bf16 v[20:23], v[132:135], v[188:191], v[20:23]
	v_mfma_f32_16x16x32_bf16 v[12:15], v[140:143], v[188:191], v[12:15]
	v_mfma_f32_16x16x32_bf16 v[40:43], v[144:147], v[160:163], v[40:43]
	v_mfma_f32_16x16x32_bf16 v[32:35], v[152:155], v[160:163], v[32:35]
	v_mfma_f32_16x16x32_bf16 v[28:31], v[144:147], v[168:171], v[28:31]
	v_mfma_f32_16x16x32_bf16 v[24:27], v[152:155], v[168:171], v[24:27]
	v_mfma_f32_16x16x32_bf16 v[16:19], v[144:147], v[176:179], v[16:19]
	v_mfma_f32_16x16x32_bf16 v[8:11], v[152:155], v[176:179], v[8:11]
	v_mfma_f32_16x16x32_bf16 v[4:7], v[144:147], v[184:187], v[4:7]
	v_mfma_f32_16x16x32_bf16 v[0:3], v[152:155], v[184:187], v[0:3]
	v_mfma_f32_16x16x32_bf16 v[40:43], v[148:151], v[164:167], v[40:43]
	v_mfma_f32_16x16x32_bf16 v[32:35], v[156:159], v[164:167], v[32:35]
	v_mfma_f32_16x16x32_bf16 v[28:31], v[148:151], v[172:175], v[28:31]
	v_mfma_f32_16x16x32_bf16 v[24:27], v[156:159], v[172:175], v[24:27]
	v_mfma_f32_16x16x32_bf16 v[16:19], v[148:151], v[180:183], v[16:19]
	v_mfma_f32_16x16x32_bf16 v[8:11], v[156:159], v[180:183], v[8:11]
	v_mfma_f32_16x16x32_bf16 v[4:7], v[148:151], v[188:191], v[4:7]
	v_mfma_f32_16x16x32_bf16 v[0:3], v[156:159], v[188:191], v[0:3]
	s_barrier
	s_add_i32 s47, 0, 0x18000
	s_add_i32 s48, 0, 0x1c000
	v_add_u32_e32 v140, s47, v238
	v_add_u32_e32 v156, s48, v238
	ds_read_b128 v[128:131], v140
	ds_read_b128 v[132:135], v140 offset:1024
	ds_read_b128 v[136:139], v140 offset:2048
	ds_read_b128 v[140:143], v140 offset:3072
	ds_read_b128 v[144:147], v156
	ds_read_b128 v[148:151], v156 offset:1024
	ds_read_b128 v[152:155], v156 offset:2048
	ds_read_b128 v[156:159], v156 offset:3072
	s_add_u32 s22, s22, 0xb0000
	s_addc_u32 s23, s23, 0
	s_mov_b32 m0, s31
	v_lshl_add_u64 v[200:201], s[22:23], 0, v[210:211]
	ds_read_b128 v[160:163], v242 offset:32768
	ds_read_b128 v[164:167], v242 offset:33792
	ds_read_b128 v[168:171], v242 offset:34816
	ds_read_b128 v[172:175], v242 offset:35840
	ds_read_b128 v[176:179], v242 offset:36864
	ds_read_b128 v[180:183], v242 offset:37888
	ds_read_b128 v[184:187], v242 offset:38912
	ds_read_b128 v[188:191], v242 offset:39936
	global_load_lds_dwordx4 v[200:201], off
	v_lshl_add_u64 v[200:201], s[22:23], 0, v[214:215]
	s_mov_b32 m0, s33
	s_nop 0
	global_load_lds_dwordx4 v[200:201], off
	s_waitcnt vmcnt(8)
	s_waitcnt lgkmcnt(0)
	s_barrier
	s_waitcnt lgkmcnt(0)
	v_mfma_f32_16x16x32_bf16 v[124:127], v[128:131], v[160:163], v[124:127]
	v_mfma_f32_16x16x32_bf16 v[120:123], v[136:139], v[160:163], v[120:123]
	v_mfma_f32_16x16x32_bf16 v[116:119], v[128:131], v[168:171], v[116:119]
	v_mfma_f32_16x16x32_bf16 v[112:115], v[136:139], v[168:171], v[112:115]
	v_mfma_f32_16x16x32_bf16 v[108:111], v[128:131], v[176:179], v[108:111]
	v_mfma_f32_16x16x32_bf16 v[100:103], v[136:139], v[176:179], v[100:103]
	v_mfma_f32_16x16x32_bf16 v[80:83], v[128:131], v[184:187], v[80:83]
	v_mfma_f32_16x16x32_bf16 v[72:75], v[136:139], v[184:187], v[72:75]
	v_mfma_f32_16x16x32_bf16 v[124:127], v[132:135], v[164:167], v[124:127]
	v_mfma_f32_16x16x32_bf16 v[120:123], v[140:143], v[164:167], v[120:123]
	v_mfma_f32_16x16x32_bf16 v[116:119], v[132:135], v[172:175], v[116:119]
	v_mfma_f32_16x16x32_bf16 v[112:115], v[140:143], v[172:175], v[112:115]
	v_mfma_f32_16x16x32_bf16 v[108:111], v[132:135], v[180:183], v[108:111]
	v_mfma_f32_16x16x32_bf16 v[100:103], v[140:143], v[180:183], v[100:103]
	v_mfma_f32_16x16x32_bf16 v[80:83], v[132:135], v[188:191], v[80:83]
	v_mfma_f32_16x16x32_bf16 v[72:75], v[140:143], v[188:191], v[72:75]
	v_mfma_f32_16x16x32_bf16 v[104:107], v[144:147], v[160:163], v[104:107]
	v_mfma_f32_16x16x32_bf16 v[96:99], v[152:155], v[160:163], v[96:99]
	v_mfma_f32_16x16x32_bf16 v[92:95], v[144:147], v[168:171], v[92:95]
	v_mfma_f32_16x16x32_bf16 v[88:91], v[152:155], v[168:171], v[88:91]
	v_mfma_f32_16x16x32_bf16 v[84:87], v[144:147], v[176:179], v[84:87]
	v_mfma_f32_16x16x32_bf16 v[76:79], v[152:155], v[176:179], v[76:79]
	v_mfma_f32_16x16x32_bf16 v[68:71], v[144:147], v[184:187], v[68:71]
	v_mfma_f32_16x16x32_bf16 v[64:67], v[152:155], v[184:187], v[64:67]
	v_mfma_f32_16x16x32_bf16 v[104:107], v[148:151], v[164:167], v[104:107]
	v_mfma_f32_16x16x32_bf16 v[96:99], v[156:159], v[164:167], v[96:99]
	v_mfma_f32_16x16x32_bf16 v[92:95], v[148:151], v[172:175], v[92:95]
	v_mfma_f32_16x16x32_bf16 v[88:91], v[156:159], v[172:175], v[88:91]
	v_mfma_f32_16x16x32_bf16 v[84:87], v[148:151], v[180:183], v[84:87]
	v_mfma_f32_16x16x32_bf16 v[76:79], v[156:159], v[180:183], v[76:79]
	v_mfma_f32_16x16x32_bf16 v[68:71], v[148:151], v[188:191], v[68:71]
	v_mfma_f32_16x16x32_bf16 v[64:67], v[156:159], v[188:191], v[64:67]
	s_barrier
	s_add_i32 s22, s47, s28
	v_lshl_add_u64 v[192:193], v[192:193], 0, s[16:17]
	s_mov_b32 m0, s22
	ds_read_b128 v[160:163], v242 offset:49152
	ds_read_b128 v[164:167], v242 offset:50176
	ds_read_b128 v[168:171], v242 offset:51200
	ds_read_b128 v[172:175], v242 offset:52224
	ds_read_b128 v[176:179], v242 offset:53248
	ds_read_b128 v[180:183], v242 offset:54272
	ds_read_b128 v[184:187], v242 offset:55296
	ds_read_b128 v[188:191], v242 offset:56320
	global_load_lds_dwordx4 v[192:193], off
	s_add_i32 m0, s22, 0x2000
	s_add_u32 s20, s20, 0xb0080
	v_lshl_add_u64 v[192:193], v[194:195], 0, s[16:17]
	s_addc_u32 s21, s21, 0
	s_add_i32 s22, s48, s28
	global_load_lds_dwordx4 v[192:193], off
	v_lshl_add_u64 v[192:193], s[20:21], 0, v[212:213]
	s_mov_b32 m0, s22
	s_nop 0
	global_load_lds_dwordx4 v[192:193], off
	v_lshl_add_u64 v[192:193], s[20:21], 0, v[216:217]
	s_add_i32 m0, s22, 0x2000
	s_nop 0
	global_load_lds_dwordx4 v[192:193], off
	v_lshl_add_u64 v[192:193], v[196:197], 0, s[16:17]
	s_mov_b32 m0, s35
	s_nop 0
	global_load_lds_dwordx4 v[192:193], off
	v_lshl_add_u64 v[192:193], v[198:199], 0, s[16:17]
	s_mov_b32 m0, s36
	s_nop 0
	global_load_lds_dwordx4 v[192:193], off
	s_waitcnt vmcnt(8)
	s_waitcnt lgkmcnt(0)
	s_barrier
	s_waitcnt lgkmcnt(0)
	v_mfma_f32_16x16x32_bf16 v[60:63], v[128:131], v[160:163], v[60:63]
	v_mfma_f32_16x16x32_bf16 v[56:59], v[136:139], v[160:163], v[56:59]
	v_mfma_f32_16x16x32_bf16 v[52:55], v[128:131], v[168:171], v[52:55]
	v_mfma_f32_16x16x32_bf16 v[48:51], v[136:139], v[168:171], v[48:51]
	v_mfma_f32_16x16x32_bf16 v[44:47], v[128:131], v[176:179], v[44:47]
	v_mfma_f32_16x16x32_bf16 v[36:39], v[136:139], v[176:179], v[36:39]
	v_mfma_f32_16x16x32_bf16 v[20:23], v[128:131], v[184:187], v[20:23]
	v_mfma_f32_16x16x32_bf16 v[12:15], v[136:139], v[184:187], v[12:15]
	v_mfma_f32_16x16x32_bf16 v[60:63], v[132:135], v[164:167], v[60:63]
	v_mfma_f32_16x16x32_bf16 v[56:59], v[140:143], v[164:167], v[56:59]
	v_mfma_f32_16x16x32_bf16 v[52:55], v[132:135], v[172:175], v[52:55]
	v_mfma_f32_16x16x32_bf16 v[48:51], v[140:143], v[172:175], v[48:51]
	v_mfma_f32_16x16x32_bf16 v[44:47], v[132:135], v[180:183], v[44:47]
	v_mfma_f32_16x16x32_bf16 v[36:39], v[140:143], v[180:183], v[36:39]
	v_mfma_f32_16x16x32_bf16 v[20:23], v[132:135], v[188:191], v[20:23]
	v_mfma_f32_16x16x32_bf16 v[12:15], v[140:143], v[188:191], v[12:15]
	v_mfma_f32_16x16x32_bf16 v[40:43], v[144:147], v[160:163], v[40:43]
	v_mfma_f32_16x16x32_bf16 v[32:35], v[152:155], v[160:163], v[32:35]
	v_mfma_f32_16x16x32_bf16 v[28:31], v[144:147], v[168:171], v[28:31]
	v_mfma_f32_16x16x32_bf16 v[24:27], v[152:155], v[168:171], v[24:27]
	v_mfma_f32_16x16x32_bf16 v[16:19], v[144:147], v[176:179], v[16:19]
	v_mfma_f32_16x16x32_bf16 v[8:11], v[152:155], v[176:179], v[8:11]
	v_mfma_f32_16x16x32_bf16 v[4:7], v[144:147], v[184:187], v[4:7]
	v_mfma_f32_16x16x32_bf16 v[0:3], v[152:155], v[184:187], v[0:3]
	v_mfma_f32_16x16x32_bf16 v[40:43], v[148:151], v[164:167], v[40:43]
	v_mfma_f32_16x16x32_bf16 v[32:35], v[156:159], v[164:167], v[32:35]
	v_mfma_f32_16x16x32_bf16 v[28:31], v[148:151], v[172:175], v[28:31]
	v_mfma_f32_16x16x32_bf16 v[24:27], v[156:159], v[172:175], v[24:27]
	v_mfma_f32_16x16x32_bf16 v[16:19], v[148:151], v[180:183], v[16:19]
	v_mfma_f32_16x16x32_bf16 v[8:11], v[156:159], v[180:183], v[8:11]
	v_mfma_f32_16x16x32_bf16 v[4:7], v[148:151], v[188:191], v[4:7]
	v_mfma_f32_16x16x32_bf16 v[0:3], v[156:159], v[188:191], v[0:3]
	s_barrier
	s_add_i32 s46, s46, 2
	s_add_u32 s4, s4, 0x100
	s_addc_u32 s5, s5, 0
	s_add_u32 s44, s44, 0x100
	s_addc_u32 s45, s45, 0
	s_cmp_gt_u32 s46, 41
	s_cbranch_scc0 .LBB0_1318
	s_cmp_gt_i32 s24, 63
	s_cselect_b64 s[20:21], -1, 0
	s_lshl_b32 s4, s24, 2
	s_add_i32 s45, s37, s4
	s_ashr_i32 s44, s24, 3
	s_cmp_lt_i32 s24, 64
	s_cselect_b64 s[4:5], -1, 0
	s_and_b64 vcc, s[4:5], exec
	s_cselect_b32 s22, s44, s45
	v_lshl_or_b32 v128, s25, 8, v239
	v_lshl_add_u32 v228, s24, 8, v237
	s_mul_i32 s24, s22, 0x9000
	v_ashrrev_i32_e32 v129, 31, v128
	v_add_u32_e32 v130, 0xffffc000, v228
	s_mul_hi_i32 s25, s22, 0x9000
	s_cselect_b32 s23, s73, s9
	s_cselect_b32 s22, s72, s8
	s_add_u32 s24, s12, s24
	v_or_b32_e32 v230, 16, v228
	v_add_u32_e32 v140, 0xffffc010, v228
	v_or_b32_e32 v232, 32, v228
	v_add_u32_e32 v156, 0xffffc020, v228
	v_cndmask_b32_e64 v130, v130, v228, s[4:5]
	s_addc_u32 s25, s13, s25
	v_lshlrev_b64 v[226:227], 2, v[128:129]
	v_cndmask_b32_e64 v140, v140, v230, s[4:5]
	v_cndmask_b32_e64 v156, v156, v232, s[4:5]
	v_lshl_add_u64 v[128:129], s[24:25], 0, v[226:227]
	v_ashrrev_i32_e32 v131, 31, v130
	v_ashrrev_i32_e32 v141, 31, v140
	v_ashrrev_i32_e32 v157, 31, v156
	global_load_dwordx4 v[196:199], v[128:129], off offset:16
	global_load_dwordx4 v[204:207], v[128:129], off
	global_load_dwordx4 v[192:195], v[128:129], off offset:528
	global_load_dwordx4 v[200:203], v[128:129], off offset:512
	v_lshlrev_b64 v[128:129], 12, v[130:131]
	v_lshlrev_b64 v[140:141], 12, v[140:141]
	v_lshlrev_b64 v[156:157], 12, v[156:157]
	v_lshl_add_u64 v[128:129], s[22:23], 0, v[128:129]
	v_lshl_add_u64 v[140:141], s[22:23], 0, v[140:141]
	v_lshl_add_u64 v[156:157], s[22:23], 0, v[156:157]
	v_lshl_add_u64 v[136:137], v[128:129], 0, v[226:227]
	v_lshl_add_u64 v[152:153], v[140:141], 0, v[226:227]
	v_lshl_add_u64 v[168:169], v[156:157], 0, v[226:227]
	global_load_dwordx4 v[132:135], v[136:137], off offset:16
	global_load_dwordx4 v[144:147], v[136:137], off
	global_load_dwordx4 v[128:131], v[136:137], off offset:528
	s_nop 0
	global_load_dwordx4 v[136:139], v[136:137], off offset:512
	s_nop 0
	global_load_dwordx4 v[148:151], v[152:153], off offset:16
	global_load_dwordx4 v[160:163], v[152:153], off
	global_load_dwordx4 v[140:143], v[152:153], off offset:528
	s_nop 0
	global_load_dwordx4 v[152:155], v[152:153], off offset:512
	s_nop 0
	global_load_dwordx4 v[164:167], v[168:169], off offset:16
	global_load_dwordx4 v[172:175], v[168:169], off
	global_load_dwordx4 v[156:159], v[168:169], off offset:528
	s_nop 0
	global_load_dwordx4 v[168:171], v[168:169], off offset:512
	v_or_b32_e32 v178, 48, v228
	s_mov_b64 s[24:25], -1
	v_ashrrev_i32_e32 v179, 31, v178
	s_cbranch_vccnz .LBB0_1321
	v_add_u32_e32 v176, 0xffffc030, v228
	v_ashrrev_i32_e32 v177, 31, v176
	v_lshlrev_b64 v[176:177], 12, v[176:177]
	v_lshl_add_u64 v[176:177], s[8:9], 0, v[176:177]
	v_lshlrev_b64 v[234:235], 12, v[178:179]
	s_mov_b64 s[24:25], 0
